# code placement: every MFMA of the GEMM compute loops padded to an 8-byte aligned address
# baseline (speedup 1.0000x reference)
.Lgm_f1_loop:
	s_barrier
	s_cmp_eq_u32 s34, 0
	s_cbranch_scc1 .Lgm_f1_first
	s_nop 0
	v_mfma_f32_16x16x32_bf16 v[4:7], v[140:143], v[164:167], v[4:7]
	ds_read_b128 v[100:103], v199 offset:0
	v_mfma_f32_16x16x32_bf16 v[20:23], v[144:147], v[164:167], v[20:23]
	ds_read_b128 v[104:107], v199 offset:2048
	v_mfma_f32_16x16x32_bf16 v[36:39], v[148:151], v[164:167], v[36:39]
	ds_read_b128 v[108:111], v199 offset:4096
	v_mfma_f32_16x16x32_bf16 v[52:55], v[152:155], v[164:167], v[52:55]
	ds_read_b128 v[112:115], v199 offset:6144
	v_mfma_f32_16x16x32_bf16 v[68:71], v[156:159], v[164:167], v[68:71]
	ds_read_b128 v[116:119], v199 offset:8192
	v_mfma_f32_16x16x32_bf16 v[84:87], v[160:163], v[164:167], v[84:87]
	ds_read_b128 v[120:123], v199 offset:10240
	v_mfma_f32_16x16x32_bf16 v[8:11], v[140:143], v[168:171], v[8:11]
	ds_read_b128 v[124:127], v201 offset:0
	v_mfma_f32_16x16x32_bf16 v[24:27], v[144:147], v[168:171], v[24:27]
	ds_read_b128 v[128:131], v201 offset:2048
	v_mfma_f32_16x16x32_bf16 v[40:43], v[148:151], v[168:171], v[40:43]
	ds_read_b128 v[132:135], v201 offset:4096
	v_mfma_f32_16x16x32_bf16 v[56:59], v[152:155], v[168:171], v[56:59]
	ds_read_b128 v[136:139], v201 offset:6144
	v_mfma_f32_16x16x32_bf16 v[72:75], v[156:159], v[168:171], v[72:75]
	v_mfma_f32_16x16x32_bf16 v[88:91], v[160:163], v[168:171], v[88:91]
	v_mfma_f32_16x16x32_bf16 v[12:15], v[140:143], v[172:175], v[12:15]
	v_mfma_f32_16x16x32_bf16 v[28:31], v[144:147], v[172:175], v[28:31]
	v_mfma_f32_16x16x32_bf16 v[44:47], v[148:151], v[172:175], v[44:47]
	v_mfma_f32_16x16x32_bf16 v[60:63], v[152:155], v[172:175], v[60:63]
	v_mfma_f32_16x16x32_bf16 v[76:79], v[156:159], v[172:175], v[76:79]
	v_mfma_f32_16x16x32_bf16 v[92:95], v[160:163], v[172:175], v[92:95]
	v_mfma_f32_16x16x32_bf16 v[16:19], v[140:143], v[176:179], v[16:19]
	ds_read_b128 v[140:143], v200 offset:0
	v_mfma_f32_16x16x32_bf16 v[32:35], v[144:147], v[176:179], v[32:35]
	ds_read_b128 v[144:147], v200 offset:2048
	v_mfma_f32_16x16x32_bf16 v[48:51], v[148:151], v[176:179], v[48:51]
	ds_read_b128 v[148:151], v200 offset:4096
	v_mfma_f32_16x16x32_bf16 v[64:67], v[152:155], v[176:179], v[64:67]
	ds_read_b128 v[152:155], v200 offset:6144
	v_mfma_f32_16x16x32_bf16 v[80:83], v[156:159], v[176:179], v[80:83]
	ds_read_b128 v[156:159], v200 offset:8192
	v_mfma_f32_16x16x32_bf16 v[96:99], v[160:163], v[176:179], v[96:99]
	ds_read_b128 v[160:163], v200 offset:10240
	ds_read_b128 v[164:167], v202 offset:0
	ds_read_b128 v[168:171], v202 offset:2048
	ds_read_b128 v[172:175], v202 offset:4096
	ds_read_b128 v[176:179], v202 offset:6144
	s_branch .Lgm_f1_join

.Lgm_f1_join:
	s_waitcnt lgkmcnt(13)
	v_mfma_f32_16x16x32_bf16 v[4:7], v[100:103], v[124:127], v[4:7]
	v_mfma_f32_16x16x32_bf16 v[20:23], v[104:107], v[124:127], v[20:23]
	v_mfma_f32_16x16x32_bf16 v[36:39], v[108:111], v[124:127], v[36:39]
	v_mfma_f32_16x16x32_bf16 v[52:55], v[112:115], v[124:127], v[52:55]
	v_mfma_f32_16x16x32_bf16 v[68:71], v[116:119], v[124:127], v[68:71]
	v_mfma_f32_16x16x32_bf16 v[84:87], v[120:123], v[124:127], v[84:87]
	s_waitcnt lgkmcnt(12)
	s_nop 0
	v_mfma_f32_16x16x32_bf16 v[8:11], v[100:103], v[128:131], v[8:11]
	v_mfma_f32_16x16x32_bf16 v[24:27], v[104:107], v[128:131], v[24:27]
	v_mfma_f32_16x16x32_bf16 v[40:43], v[108:111], v[128:131], v[40:43]
	v_mfma_f32_16x16x32_bf16 v[56:59], v[112:115], v[128:131], v[56:59]
	v_mfma_f32_16x16x32_bf16 v[72:75], v[116:119], v[128:131], v[72:75]
	v_mfma_f32_16x16x32_bf16 v[88:91], v[120:123], v[128:131], v[88:91]
	s_waitcnt lgkmcnt(11)
	s_nop 0
	v_mfma_f32_16x16x32_bf16 v[12:15], v[100:103], v[132:135], v[12:15]
	v_mfma_f32_16x16x32_bf16 v[28:31], v[104:107], v[132:135], v[28:31]
	v_mfma_f32_16x16x32_bf16 v[44:47], v[108:111], v[132:135], v[44:47]
	v_mfma_f32_16x16x32_bf16 v[60:63], v[112:115], v[132:135], v[60:63]
	v_mfma_f32_16x16x32_bf16 v[76:79], v[116:119], v[132:135], v[76:79]
	v_mfma_f32_16x16x32_bf16 v[92:95], v[120:123], v[132:135], v[92:95]
	s_waitcnt lgkmcnt(10)
	s_nop 0
	v_mfma_f32_16x16x32_bf16 v[16:19], v[100:103], v[136:139], v[16:19]
	v_mfma_f32_16x16x32_bf16 v[32:35], v[104:107], v[136:139], v[32:35]
	v_mfma_f32_16x16x32_bf16 v[48:51], v[108:111], v[136:139], v[48:51]
	v_mfma_f32_16x16x32_bf16 v[64:67], v[112:115], v[136:139], v[64:67]
	v_mfma_f32_16x16x32_bf16 v[80:83], v[116:119], v[136:139], v[80:83]
	v_mfma_f32_16x16x32_bf16 v[96:99], v[120:123], v[136:139], v[96:99]
	s_waitcnt lgkmcnt(0)
	s_add_u32 s34, s34, 1
	s_add_u32 s31, s31, 1
	s_cmp_lt_u32 s34, 16
	s_cbranch_scc1 .Lgm_f1_rot
	s_nop 0
	v_mfma_f32_16x16x32_bf16 v[4:7], v[140:143], v[164:167], v[4:7]
	v_mfma_f32_16x16x32_bf16 v[20:23], v[144:147], v[164:167], v[20:23]
	v_mfma_f32_16x16x32_bf16 v[36:39], v[148:151], v[164:167], v[36:39]
	v_mfma_f32_16x16x32_bf16 v[52:55], v[152:155], v[164:167], v[52:55]
	v_mfma_f32_16x16x32_bf16 v[68:71], v[156:159], v[164:167], v[68:71]
	v_mfma_f32_16x16x32_bf16 v[84:87], v[160:163], v[164:167], v[84:87]
	v_mfma_f32_16x16x32_bf16 v[8:11], v[140:143], v[168:171], v[8:11]
	v_mfma_f32_16x16x32_bf16 v[24:27], v[144:147], v[168:171], v[24:27]
	v_mfma_f32_16x16x32_bf16 v[40:43], v[148:151], v[168:171], v[40:43]
	v_mfma_f32_16x16x32_bf16 v[56:59], v[152:155], v[168:171], v[56:59]
	v_mfma_f32_16x16x32_bf16 v[72:75], v[156:159], v[168:171], v[72:75]
	v_mfma_f32_16x16x32_bf16 v[88:91], v[160:163], v[168:171], v[88:91]
	v_mfma_f32_16x16x32_bf16 v[12:15], v[140:143], v[172:175], v[12:15]
	v_mfma_f32_16x16x32_bf16 v[28:31], v[144:147], v[172:175], v[28:31]
	v_mfma_f32_16x16x32_bf16 v[44:47], v[148:151], v[172:175], v[44:47]
	v_mfma_f32_16x16x32_bf16 v[60:63], v[152:155], v[172:175], v[60:63]
	v_mfma_f32_16x16x32_bf16 v[76:79], v[156:159], v[172:175], v[76:79]
	v_mfma_f32_16x16x32_bf16 v[92:95], v[160:163], v[172:175], v[92:95]
	v_mfma_f32_16x16x32_bf16 v[16:19], v[140:143], v[176:179], v[16:19]
	v_mfma_f32_16x16x32_bf16 v[32:35], v[144:147], v[176:179], v[32:35]
	v_mfma_f32_16x16x32_bf16 v[48:51], v[148:151], v[176:179], v[48:51]
	v_mfma_f32_16x16x32_bf16 v[64:67], v[152:155], v[176:179], v[64:67]
	v_mfma_f32_16x16x32_bf16 v[80:83], v[156:159], v[176:179], v[80:83]
	v_mfma_f32_16x16x32_bf16 v[96:99], v[160:163], v[176:179], v[96:99]
	s_and_b32 s6, s35, 31
	s_mul_i32 s6, s6, 192
	s_lshr_b32 s7, s35, 5
	s_lshl_b32 s7, s7, 7
	s_nop 7
	s_mul_i32 s4, s6, 0x2000
	s_lshl_b32 s5, s7, 1
	s_add_u32 s4, s4, s5
	v_add_u32_e32 v197, s4, v205
	ds_write_b32 v203, v4 offset:0
	ds_write_b32 v203, v5 offset:272
	ds_write_b32 v203, v6 offset:544
	ds_write_b32 v203, v7 offset:816
	ds_write_b32 v203, v8 offset:64
	ds_write_b32 v203, v9 offset:336
	ds_write_b32 v203, v10 offset:608
	ds_write_b32 v203, v11 offset:880
	ds_write_b32 v203, v12 offset:128
	ds_write_b32 v203, v13 offset:400
	ds_write_b32 v203, v14 offset:672
	ds_write_b32 v203, v15 offset:944
	ds_write_b32 v203, v16 offset:192
	ds_write_b32 v203, v17 offset:464
	ds_write_b32 v203, v18 offset:736
	ds_write_b32 v203, v19 offset:1008
	s_waitcnt lgkmcnt(0)
	ds_read_b128 v[156:159], v204 offset:0
	ds_read_b128 v[160:163], v204 offset:1088
	ds_read_b128 v[164:167], v204 offset:2176
	ds_read_b128 v[168:171], v204 offset:3264
	s_waitcnt lgkmcnt(3)
	v_max_f32_e32 v156, 0, v156
	v_max_f32_e32 v157, 0, v157
	v_max_f32_e32 v158, 0, v158
	v_max_f32_e32 v159, 0, v159
	v_mul_f32_e32 v156, v156, v156
	v_mul_f32_e32 v157, v157, v157
	v_mul_f32_e32 v158, v158, v158
	v_mul_f32_e32 v159, v159, v159
	v_cvt_pk_bf16_f32 v176, v156, v157
	v_cvt_pk_bf16_f32 v177, v158, v159
	global_store_dwordx2 v197, v[176:177], s[56:57] sc0 sc1
	v_add_u32_e32 v197, 0x8000, v197
	s_waitcnt lgkmcnt(2)
	v_max_f32_e32 v160, 0, v160
	v_max_f32_e32 v161, 0, v161
	v_max_f32_e32 v162, 0, v162
	v_max_f32_e32 v163, 0, v163
	v_mul_f32_e32 v160, v160, v160
	v_mul_f32_e32 v161, v161, v161
	v_mul_f32_e32 v162, v162, v162
	v_mul_f32_e32 v163, v163, v163
	v_cvt_pk_bf16_f32 v178, v160, v161
	v_cvt_pk_bf16_f32 v179, v162, v163
	global_store_dwordx2 v197, v[178:179], s[56:57] sc0 sc1
	v_add_u32_e32 v197, 0x8000, v197
	s_waitcnt lgkmcnt(1)
	v_max_f32_e32 v164, 0, v164
	v_max_f32_e32 v165, 0, v165
	v_max_f32_e32 v166, 0, v166
	v_max_f32_e32 v167, 0, v167
	v_mul_f32_e32 v164, v164, v164
	v_mul_f32_e32 v165, v165, v165
	v_mul_f32_e32 v166, v166, v166
	v_mul_f32_e32 v167, v167, v167
	v_cvt_pk_bf16_f32 v176, v164, v165
	v_cvt_pk_bf16_f32 v177, v166, v167
	global_store_dwordx2 v197, v[176:177], s[56:57] sc0 sc1
	v_add_u32_e32 v197, 0x8000, v197
	s_waitcnt lgkmcnt(0)
	v_max_f32_e32 v168, 0, v168
	v_max_f32_e32 v169, 0, v169
	v_max_f32_e32 v170, 0, v170
	v_max_f32_e32 v171, 0, v171
	v_mul_f32_e32 v168, v168, v168
	v_mul_f32_e32 v169, v169, v169
	v_mul_f32_e32 v170, v170, v170
	v_mul_f32_e32 v171, v171, v171
	v_cvt_pk_bf16_f32 v178, v168, v169
	v_cvt_pk_bf16_f32 v179, v170, v171
	global_store_dwordx2 v197, v[178:179], s[56:57] sc0 sc1
	v_add_u32_e32 v197, 0x8000, v197
	ds_write_b32 v203, v20 offset:0
	ds_write_b32 v203, v21 offset:272
	ds_write_b32 v203, v22 offset:544
	ds_write_b32 v203, v23 offset:816
	ds_write_b32 v203, v24 offset:64
	ds_write_b32 v203, v25 offset:336
	ds_write_b32 v203, v26 offset:608
	ds_write_b32 v203, v27 offset:880
	ds_write_b32 v203, v28 offset:128
	ds_write_b32 v203, v29 offset:400
	ds_write_b32 v203, v30 offset:672
	ds_write_b32 v203, v31 offset:944
	ds_write_b32 v203, v32 offset:192
	ds_write_b32 v203, v33 offset:464
	ds_write_b32 v203, v34 offset:736
	ds_write_b32 v203, v35 offset:1008
	s_waitcnt lgkmcnt(0)
	ds_read_b128 v[156:159], v204 offset:0
	ds_read_b128 v[160:163], v204 offset:1088
	ds_read_b128 v[164:167], v204 offset:2176
	ds_read_b128 v[168:171], v204 offset:3264
	s_waitcnt lgkmcnt(3)
	v_max_f32_e32 v156, 0, v156
	v_max_f32_e32 v157, 0, v157
	v_max_f32_e32 v158, 0, v158
	v_max_f32_e32 v159, 0, v159
	v_mul_f32_e32 v156, v156, v156
	v_mul_f32_e32 v157, v157, v157
	v_mul_f32_e32 v158, v158, v158
	v_mul_f32_e32 v159, v159, v159
	v_cvt_pk_bf16_f32 v176, v156, v157
	v_cvt_pk_bf16_f32 v177, v158, v159
	global_store_dwordx2 v197, v[176:177], s[56:57] sc0 sc1
	v_add_u32_e32 v197, 0x8000, v197
	s_waitcnt lgkmcnt(2)
	v_max_f32_e32 v160, 0, v160
	v_max_f32_e32 v161, 0, v161
	v_max_f32_e32 v162, 0, v162
	v_max_f32_e32 v163, 0, v163
	v_mul_f32_e32 v160, v160, v160
	v_mul_f32_e32 v161, v161, v161
	v_mul_f32_e32 v162, v162, v162
	v_mul_f32_e32 v163, v163, v163
	v_cvt_pk_bf16_f32 v178, v160, v161
	v_cvt_pk_bf16_f32 v179, v162, v163
	global_store_dwordx2 v197, v[178:179], s[56:57] sc0 sc1
	v_add_u32_e32 v197, 0x8000, v197
	s_waitcnt lgkmcnt(1)
	v_max_f32_e32 v164, 0, v164
	v_max_f32_e32 v165, 0, v165
	v_max_f32_e32 v166, 0, v166
	v_max_f32_e32 v167, 0, v167
	v_mul_f32_e32 v164, v164, v164
	v_mul_f32_e32 v165, v165, v165
	v_mul_f32_e32 v166, v166, v166
	v_mul_f32_e32 v167, v167, v167
	v_cvt_pk_bf16_f32 v176, v164, v165
	v_cvt_pk_bf16_f32 v177, v166, v167
	global_store_dwordx2 v197, v[176:177], s[56:57] sc0 sc1
	v_add_u32_e32 v197, 0x8000, v197
	s_waitcnt lgkmcnt(0)
	v_max_f32_e32 v168, 0, v168
	v_max_f32_e32 v169, 0, v169
	v_max_f32_e32 v170, 0, v170
	v_max_f32_e32 v171, 0, v171
	v_mul_f32_e32 v168, v168, v168
	v_mul_f32_e32 v169, v169, v169
	v_mul_f32_e32 v170, v170, v170
	v_mul_f32_e32 v171, v171, v171
	v_cvt_pk_bf16_f32 v178, v168, v169
	v_cvt_pk_bf16_f32 v179, v170, v171
	global_store_dwordx2 v197, v[178:179], s[56:57] sc0 sc1
	v_add_u32_e32 v197, 0x8000, v197
	ds_write_b32 v203, v36 offset:0
	ds_write_b32 v203, v37 offset:272
	ds_write_b32 v203, v38 offset:544
	ds_write_b32 v203, v39 offset:816
	ds_write_b32 v203, v40 offset:64
	ds_write_b32 v203, v41 offset:336
	ds_write_b32 v203, v42 offset:608
	ds_write_b32 v203, v43 offset:880
	ds_write_b32 v203, v44 offset:128
	ds_write_b32 v203, v45 offset:400
	ds_write_b32 v203, v46 offset:672
	ds_write_b32 v203, v47 offset:944
	ds_write_b32 v203, v48 offset:192
	ds_write_b32 v203, v49 offset:464
	ds_write_b32 v203, v50 offset:736
	ds_write_b32 v203, v51 offset:1008
	s_waitcnt lgkmcnt(0)
	ds_read_b128 v[156:159], v204 offset:0
	ds_read_b128 v[160:163], v204 offset:1088
	ds_read_b128 v[164:167], v204 offset:2176
	ds_read_b128 v[168:171], v204 offset:3264
	s_waitcnt lgkmcnt(3)
	v_max_f32_e32 v156, 0, v156
	v_max_f32_e32 v157, 0, v157
	v_max_f32_e32 v158, 0, v158
	v_max_f32_e32 v159, 0, v159
	v_mul_f32_e32 v156, v156, v156
	v_mul_f32_e32 v157, v157, v157
	v_mul_f32_e32 v158, v158, v158
	v_mul_f32_e32 v159, v159, v159
	v_cvt_pk_bf16_f32 v176, v156, v157
	v_cvt_pk_bf16_f32 v177, v158, v159
	global_store_dwordx2 v197, v[176:177], s[56:57] sc0 sc1
	v_add_u32_e32 v197, 0x8000, v197
	s_waitcnt lgkmcnt(2)
	v_max_f32_e32 v160, 0, v160
	v_max_f32_e32 v161, 0, v161
	v_max_f32_e32 v162, 0, v162
	v_max_f32_e32 v163, 0, v163
	v_mul_f32_e32 v160, v160, v160
	v_mul_f32_e32 v161, v161, v161
	v_mul_f32_e32 v162, v162, v162
	v_mul_f32_e32 v163, v163, v163
	v_cvt_pk_bf16_f32 v178, v160, v161
	v_cvt_pk_bf16_f32 v179, v162, v163
	global_store_dwordx2 v197, v[178:179], s[56:57] sc0 sc1
	v_add_u32_e32 v197, 0x8000, v197
	s_waitcnt lgkmcnt(1)
	v_max_f32_e32 v164, 0, v164
	v_max_f32_e32 v165, 0, v165
	v_max_f32_e32 v166, 0, v166
	v_max_f32_e32 v167, 0, v167
	v_mul_f32_e32 v164, v164, v164
	v_mul_f32_e32 v165, v165, v165
	v_mul_f32_e32 v166, v166, v166
	v_mul_f32_e32 v167, v167, v167
	v_cvt_pk_bf16_f32 v176, v164, v165
	v_cvt_pk_bf16_f32 v177, v166, v167
	global_store_dwordx2 v197, v[176:177], s[56:57] sc0 sc1
	v_add_u32_e32 v197, 0x8000, v197
	s_waitcnt lgkmcnt(0)
	v_max_f32_e32 v168, 0, v168
	v_max_f32_e32 v169, 0, v169
	v_max_f32_e32 v170, 0, v170
	v_max_f32_e32 v171, 0, v171
	v_mul_f32_e32 v168, v168, v168
	v_mul_f32_e32 v169, v169, v169
	v_mul_f32_e32 v170, v170, v170
	v_mul_f32_e32 v171, v171, v171
	v_cvt_pk_bf16_f32 v178, v168, v169
	v_cvt_pk_bf16_f32 v179, v170, v171
	global_store_dwordx2 v197, v[178:179], s[56:57] sc0 sc1
	v_add_u32_e32 v197, 0x8000, v197
	ds_write_b32 v203, v52 offset:0
	ds_write_b32 v203, v53 offset:272
	ds_write_b32 v203, v54 offset:544
	ds_write_b32 v203, v55 offset:816
	ds_write_b32 v203, v56 offset:64
	ds_write_b32 v203, v57 offset:336
	ds_write_b32 v203, v58 offset:608
	ds_write_b32 v203, v59 offset:880
	ds_write_b32 v203, v60 offset:128
	ds_write_b32 v203, v61 offset:400
	ds_write_b32 v203, v62 offset:672
	ds_write_b32 v203, v63 offset:944
	ds_write_b32 v203, v64 offset:192
	ds_write_b32 v203, v65 offset:464
	ds_write_b32 v203, v66 offset:736
	ds_write_b32 v203, v67 offset:1008
	s_waitcnt lgkmcnt(0)
	ds_read_b128 v[156:159], v204 offset:0
	ds_read_b128 v[160:163], v204 offset:1088
	ds_read_b128 v[164:167], v204 offset:2176
	ds_read_b128 v[168:171], v204 offset:3264
	s_waitcnt lgkmcnt(3)
	v_max_f32_e32 v156, 0, v156
	v_max_f32_e32 v157, 0, v157
	v_max_f32_e32 v158, 0, v158
	v_max_f32_e32 v159, 0, v159
	v_mul_f32_e32 v156, v156, v156
	v_mul_f32_e32 v157, v157, v157
	v_mul_f32_e32 v158, v158, v158
	v_mul_f32_e32 v159, v159, v159
	v_cvt_pk_bf16_f32 v176, v156, v157
	v_cvt_pk_bf16_f32 v177, v158, v159
	global_store_dwordx2 v197, v[176:177], s[56:57] sc0 sc1
	v_add_u32_e32 v197, 0x8000, v197
	s_waitcnt lgkmcnt(2)
	v_max_f32_e32 v160, 0, v160
	v_max_f32_e32 v161, 0, v161
	v_max_f32_e32 v162, 0, v162
	v_max_f32_e32 v163, 0, v163
	v_mul_f32_e32 v160, v160, v160
	v_mul_f32_e32 v161, v161, v161
	v_mul_f32_e32 v162, v162, v162
	v_mul_f32_e32 v163, v163, v163
	v_cvt_pk_bf16_f32 v178, v160, v161
	v_cvt_pk_bf16_f32 v179, v162, v163
	global_store_dwordx2 v197, v[178:179], s[56:57] sc0 sc1
	v_add_u32_e32 v197, 0x8000, v197
	s_waitcnt lgkmcnt(1)
	v_max_f32_e32 v164, 0, v164
	v_max_f32_e32 v165, 0, v165
	v_max_f32_e32 v166, 0, v166
	v_max_f32_e32 v167, 0, v167
	v_mul_f32_e32 v164, v164, v164
	v_mul_f32_e32 v165, v165, v165
	v_mul_f32_e32 v166, v166, v166
	v_mul_f32_e32 v167, v167, v167
	v_cvt_pk_bf16_f32 v176, v164, v165
	v_cvt_pk_bf16_f32 v177, v166, v167
	global_store_dwordx2 v197, v[176:177], s[56:57] sc0 sc1
	v_add_u32_e32 v197, 0x8000, v197
	s_waitcnt lgkmcnt(0)
	v_max_f32_e32 v168, 0, v168
	v_max_f32_e32 v169, 0, v169
	v_max_f32_e32 v170, 0, v170
	v_max_f32_e32 v171, 0, v171
	v_mul_f32_e32 v168, v168, v168
	v_mul_f32_e32 v169, v169, v169
	v_mul_f32_e32 v170, v170, v170
	v_mul_f32_e32 v171, v171, v171
	v_cvt_pk_bf16_f32 v178, v168, v169
	v_cvt_pk_bf16_f32 v179, v170, v171
	global_store_dwordx2 v197, v[178:179], s[56:57] sc0 sc1
	v_add_u32_e32 v197, 0x8000, v197
	ds_write_b32 v203, v68 offset:0
	ds_write_b32 v203, v69 offset:272
	ds_write_b32 v203, v70 offset:544
	ds_write_b32 v203, v71 offset:816
	ds_write_b32 v203, v72 offset:64
	ds_write_b32 v203, v73 offset:336
	ds_write_b32 v203, v74 offset:608
	ds_write_b32 v203, v75 offset:880
	ds_write_b32 v203, v76 offset:128
	ds_write_b32 v203, v77 offset:400
	ds_write_b32 v203, v78 offset:672
	ds_write_b32 v203, v79 offset:944
	ds_write_b32 v203, v80 offset:192
	ds_write_b32 v203, v81 offset:464
	ds_write_b32 v203, v82 offset:736
	ds_write_b32 v203, v83 offset:1008
	s_waitcnt lgkmcnt(0)
	ds_read_b128 v[156:159], v204 offset:0
	ds_read_b128 v[160:163], v204 offset:1088
	ds_read_b128 v[164:167], v204 offset:2176
	ds_read_b128 v[168:171], v204 offset:3264
	s_waitcnt lgkmcnt(3)
	v_max_f32_e32 v156, 0, v156
	v_max_f32_e32 v157, 0, v157
	v_max_f32_e32 v158, 0, v158
	v_max_f32_e32 v159, 0, v159
	v_mul_f32_e32 v156, v156, v156
	v_mul_f32_e32 v157, v157, v157
	v_mul_f32_e32 v158, v158, v158
	v_mul_f32_e32 v159, v159, v159
	v_cvt_pk_bf16_f32 v176, v156, v157
	v_cvt_pk_bf16_f32 v177, v158, v159
	global_store_dwordx2 v197, v[176:177], s[56:57] sc0 sc1
	v_add_u32_e32 v197, 0x8000, v197
	s_waitcnt lgkmcnt(2)
	v_max_f32_e32 v160, 0, v160
	v_max_f32_e32 v161, 0, v161
	v_max_f32_e32 v162, 0, v162
	v_max_f32_e32 v163, 0, v163
	v_mul_f32_e32 v160, v160, v160
	v_mul_f32_e32 v161, v161, v161
	v_mul_f32_e32 v162, v162, v162
	v_mul_f32_e32 v163, v163, v163
	v_cvt_pk_bf16_f32 v178, v160, v161
	v_cvt_pk_bf16_f32 v179, v162, v163
	global_store_dwordx2 v197, v[178:179], s[56:57] sc0 sc1
	v_add_u32_e32 v197, 0x8000, v197
	s_waitcnt lgkmcnt(1)
	v_max_f32_e32 v164, 0, v164
	v_max_f32_e32 v165, 0, v165
	v_max_f32_e32 v166, 0, v166
	v_max_f32_e32 v167, 0, v167
	v_mul_f32_e32 v164, v164, v164
	v_mul_f32_e32 v165, v165, v165
	v_mul_f32_e32 v166, v166, v166
	v_mul_f32_e32 v167, v167, v167
	v_cvt_pk_bf16_f32 v176, v164, v165
	v_cvt_pk_bf16_f32 v177, v166, v167
	global_store_dwordx2 v197, v[176:177], s[56:57] sc0 sc1
	v_add_u32_e32 v197, 0x8000, v197
	s_waitcnt lgkmcnt(0)
	v_max_f32_e32 v168, 0, v168
	v_max_f32_e32 v169, 0, v169
	v_max_f32_e32 v170, 0, v170
	v_max_f32_e32 v171, 0, v171
	v_mul_f32_e32 v168, v168, v168
	v_mul_f32_e32 v169, v169, v169
	v_mul_f32_e32 v170, v170, v170
	v_mul_f32_e32 v171, v171, v171
	v_cvt_pk_bf16_f32 v178, v168, v169
	v_cvt_pk_bf16_f32 v179, v170, v171
	global_store_dwordx2 v197, v[178:179], s[56:57] sc0 sc1
	v_add_u32_e32 v197, 0x8000, v197
	ds_write_b32 v203, v84 offset:0
	ds_write_b32 v203, v85 offset:272
	ds_write_b32 v203, v86 offset:544
	ds_write_b32 v203, v87 offset:816
	ds_write_b32 v203, v88 offset:64
	ds_write_b32 v203, v89 offset:336
	ds_write_b32 v203, v90 offset:608
	ds_write_b32 v203, v91 offset:880
	ds_write_b32 v203, v92 offset:128
	ds_write_b32 v203, v93 offset:400
	ds_write_b32 v203, v94 offset:672
	ds_write_b32 v203, v95 offset:944
	ds_write_b32 v203, v96 offset:192
	ds_write_b32 v203, v97 offset:464
	ds_write_b32 v203, v98 offset:736
	ds_write_b32 v203, v99 offset:1008
	s_waitcnt lgkmcnt(0)
	ds_read_b128 v[156:159], v204 offset:0
	ds_read_b128 v[160:163], v204 offset:1088
	ds_read_b128 v[164:167], v204 offset:2176
	ds_read_b128 v[168:171], v204 offset:3264
	s_waitcnt lgkmcnt(3)
	v_max_f32_e32 v156, 0, v156
	v_max_f32_e32 v157, 0, v157
	v_max_f32_e32 v158, 0, v158
	v_max_f32_e32 v159, 0, v159
	v_mul_f32_e32 v156, v156, v156
	v_mul_f32_e32 v157, v157, v157
	v_mul_f32_e32 v158, v158, v158
	v_mul_f32_e32 v159, v159, v159
	v_cvt_pk_bf16_f32 v176, v156, v157
	v_cvt_pk_bf16_f32 v177, v158, v159
	global_store_dwordx2 v197, v[176:177], s[56:57] sc0 sc1
	v_add_u32_e32 v197, 0x8000, v197
	s_waitcnt lgkmcnt(2)
	v_max_f32_e32 v160, 0, v160
	v_max_f32_e32 v161, 0, v161
	v_max_f32_e32 v162, 0, v162
	v_max_f32_e32 v163, 0, v163
	v_mul_f32_e32 v160, v160, v160
	v_mul_f32_e32 v161, v161, v161
	v_mul_f32_e32 v162, v162, v162
	v_mul_f32_e32 v163, v163, v163
	v_cvt_pk_bf16_f32 v178, v160, v161
	v_cvt_pk_bf16_f32 v179, v162, v163
	global_store_dwordx2 v197, v[178:179], s[56:57] sc0 sc1
	v_add_u32_e32 v197, 0x8000, v197
	s_waitcnt lgkmcnt(1)
	v_max_f32_e32 v164, 0, v164
	v_max_f32_e32 v165, 0, v165
	v_max_f32_e32 v166, 0, v166
	v_max_f32_e32 v167, 0, v167
	v_mul_f32_e32 v164, v164, v164
	v_mul_f32_e32 v165, v165, v165
	v_mul_f32_e32 v166, v166, v166
	v_mul_f32_e32 v167, v167, v167
	v_cvt_pk_bf16_f32 v176, v164, v165
	v_cvt_pk_bf16_f32 v177, v166, v167
	global_store_dwordx2 v197, v[176:177], s[56:57] sc0 sc1
	v_add_u32_e32 v197, 0x8000, v197
	s_waitcnt lgkmcnt(0)
	v_max_f32_e32 v168, 0, v168
	v_max_f32_e32 v169, 0, v169
	v_max_f32_e32 v170, 0, v170
	v_max_f32_e32 v171, 0, v171
	v_mul_f32_e32 v168, v168, v168
	v_mul_f32_e32 v169, v169, v169
	v_mul_f32_e32 v170, v170, v170
	v_mul_f32_e32 v171, v171, v171
	v_cvt_pk_bf16_f32 v178, v168, v169
	v_cvt_pk_bf16_f32 v179, v170, v171
	global_store_dwordx2 v197, v[178:179], s[56:57] sc0 sc1
	v_add_u32_e32 v197, 0x8000, v197
	v_mov_b32_e32 v4, 0
	v_mov_b32_e32 v5, 0
	v_mov_b32_e32 v6, 0
	v_mov_b32_e32 v7, 0
	v_mov_b32_e32 v8, 0
	v_mov_b32_e32 v9, 0
	v_mov_b32_e32 v10, 0
	v_mov_b32_e32 v11, 0
	v_mov_b32_e32 v12, 0
	v_mov_b32_e32 v13, 0
	v_mov_b32_e32 v14, 0
	v_mov_b32_e32 v15, 0
	v_mov_b32_e32 v16, 0
	v_mov_b32_e32 v17, 0
	v_mov_b32_e32 v18, 0
	v_mov_b32_e32 v19, 0
	v_mov_b32_e32 v20, 0
	v_mov_b32_e32 v21, 0
	v_mov_b32_e32 v22, 0
	v_mov_b32_e32 v23, 0
	v_mov_b32_e32 v24, 0
	v_mov_b32_e32 v25, 0
	v_mov_b32_e32 v26, 0
	v_mov_b32_e32 v27, 0
	v_mov_b32_e32 v28, 0
	v_mov_b32_e32 v29, 0
	v_mov_b32_e32 v30, 0
	v_mov_b32_e32 v31, 0
	v_mov_b32_e32 v32, 0
	v_mov_b32_e32 v33, 0
	v_mov_b32_e32 v34, 0
	v_mov_b32_e32 v35, 0
	v_mov_b32_e32 v36, 0
	v_mov_b32_e32 v37, 0
	v_mov_b32_e32 v38, 0
	v_mov_b32_e32 v39, 0
	v_mov_b32_e32 v40, 0
	v_mov_b32_e32 v41, 0
	v_mov_b32_e32 v42, 0
	v_mov_b32_e32 v43, 0
	v_mov_b32_e32 v44, 0
	v_mov_b32_e32 v45, 0
	v_mov_b32_e32 v46, 0
	v_mov_b32_e32 v47, 0
	v_mov_b32_e32 v48, 0
	v_mov_b32_e32 v49, 0
	v_mov_b32_e32 v50, 0
	v_mov_b32_e32 v51, 0
	v_mov_b32_e32 v52, 0
	v_mov_b32_e32 v53, 0
	v_mov_b32_e32 v54, 0
	v_mov_b32_e32 v55, 0
	v_mov_b32_e32 v56, 0
	v_mov_b32_e32 v57, 0
	v_mov_b32_e32 v58, 0
	v_mov_b32_e32 v59, 0
	v_mov_b32_e32 v60, 0
	v_mov_b32_e32 v61, 0
	v_mov_b32_e32 v62, 0
	v_mov_b32_e32 v63, 0
	v_mov_b32_e32 v64, 0
	v_mov_b32_e32 v65, 0
	v_mov_b32_e32 v66, 0
	v_mov_b32_e32 v67, 0
	v_mov_b32_e32 v68, 0
	v_mov_b32_e32 v69, 0
	v_mov_b32_e32 v70, 0
	v_mov_b32_e32 v71, 0
	v_mov_b32_e32 v72, 0
	v_mov_b32_e32 v73, 0
	v_mov_b32_e32 v74, 0
	v_mov_b32_e32 v75, 0
	v_mov_b32_e32 v76, 0
	v_mov_b32_e32 v77, 0
	v_mov_b32_e32 v78, 0
	v_mov_b32_e32 v79, 0
	v_mov_b32_e32 v80, 0
	v_mov_b32_e32 v81, 0
	v_mov_b32_e32 v82, 0
	v_mov_b32_e32 v83, 0
	v_mov_b32_e32 v84, 0
	v_mov_b32_e32 v85, 0
	v_mov_b32_e32 v86, 0
	v_mov_b32_e32 v87, 0
	v_mov_b32_e32 v88, 0
	v_mov_b32_e32 v89, 0
	v_mov_b32_e32 v90, 0
	v_mov_b32_e32 v91, 0
	v_mov_b32_e32 v92, 0
	v_mov_b32_e32 v93, 0
	v_mov_b32_e32 v94, 0
	v_mov_b32_e32 v95, 0
	v_mov_b32_e32 v96, 0
	v_mov_b32_e32 v97, 0
	v_mov_b32_e32 v98, 0
	v_mov_b32_e32 v99, 0
	s_mov_b32 s34, 0
	s_add_u32 s35, s35, s52
	s_cmp_ge_u32 s31, s30
	s_cbranch_scc1 .Lgm_f1_exit

.Lgm_f2_join:
	s_waitcnt lgkmcnt(13)
	v_mfma_f32_16x16x32_bf16 v[4:7], v[100:103], v[124:127], v[4:7]
	v_mfma_f32_16x16x32_bf16 v[20:23], v[104:107], v[124:127], v[20:23]
	v_mfma_f32_16x16x32_bf16 v[36:39], v[108:111], v[124:127], v[36:39]
	v_mfma_f32_16x16x32_bf16 v[52:55], v[112:115], v[124:127], v[52:55]
	v_mfma_f32_16x16x32_bf16 v[68:71], v[116:119], v[124:127], v[68:71]
	v_mfma_f32_16x16x32_bf16 v[84:87], v[120:123], v[124:127], v[84:87]
	s_waitcnt lgkmcnt(12)
	s_nop 0
	v_mfma_f32_16x16x32_bf16 v[8:11], v[100:103], v[128:131], v[8:11]
	v_mfma_f32_16x16x32_bf16 v[24:27], v[104:107], v[128:131], v[24:27]
	v_mfma_f32_16x16x32_bf16 v[40:43], v[108:111], v[128:131], v[40:43]
	v_mfma_f32_16x16x32_bf16 v[56:59], v[112:115], v[128:131], v[56:59]
	v_mfma_f32_16x16x32_bf16 v[72:75], v[116:119], v[128:131], v[72:75]
	v_mfma_f32_16x16x32_bf16 v[88:91], v[120:123], v[128:131], v[88:91]
	s_waitcnt lgkmcnt(11)
	s_nop 0
	v_mfma_f32_16x16x32_bf16 v[12:15], v[100:103], v[132:135], v[12:15]
	v_mfma_f32_16x16x32_bf16 v[28:31], v[104:107], v[132:135], v[28:31]
	v_mfma_f32_16x16x32_bf16 v[44:47], v[108:111], v[132:135], v[44:47]
	v_mfma_f32_16x16x32_bf16 v[60:63], v[112:115], v[132:135], v[60:63]
	v_mfma_f32_16x16x32_bf16 v[76:79], v[116:119], v[132:135], v[76:79]
	v_mfma_f32_16x16x32_bf16 v[92:95], v[120:123], v[132:135], v[92:95]
	s_waitcnt lgkmcnt(10)
	s_nop 0
	v_mfma_f32_16x16x32_bf16 v[16:19], v[100:103], v[136:139], v[16:19]
	v_mfma_f32_16x16x32_bf16 v[32:35], v[104:107], v[136:139], v[32:35]
	v_mfma_f32_16x16x32_bf16 v[48:51], v[108:111], v[136:139], v[48:51]
	v_mfma_f32_16x16x32_bf16 v[64:67], v[112:115], v[136:139], v[64:67]
	v_mfma_f32_16x16x32_bf16 v[80:83], v[116:119], v[136:139], v[80:83]
	v_mfma_f32_16x16x32_bf16 v[96:99], v[120:123], v[136:139], v[96:99]
	s_waitcnt lgkmcnt(0)
	s_add_u32 s34, s34, 1
	s_add_u32 s31, s31, 1
	s_cmp_lt_u32 s34, 64
	s_cbranch_scc1 .Lgm_f2_rot
	s_nop 0
	v_mfma_f32_16x16x32_bf16 v[4:7], v[140:143], v[164:167], v[4:7]
	v_mfma_f32_16x16x32_bf16 v[20:23], v[144:147], v[164:167], v[20:23]
	v_mfma_f32_16x16x32_bf16 v[36:39], v[148:151], v[164:167], v[36:39]
	v_mfma_f32_16x16x32_bf16 v[52:55], v[152:155], v[164:167], v[52:55]
	v_mfma_f32_16x16x32_bf16 v[68:71], v[156:159], v[164:167], v[68:71]
	v_mfma_f32_16x16x32_bf16 v[84:87], v[160:163], v[164:167], v[84:87]
	v_mfma_f32_16x16x32_bf16 v[8:11], v[140:143], v[168:171], v[8:11]
	v_mfma_f32_16x16x32_bf16 v[24:27], v[144:147], v[168:171], v[24:27]
	v_mfma_f32_16x16x32_bf16 v[40:43], v[148:151], v[168:171], v[40:43]
	v_mfma_f32_16x16x32_bf16 v[56:59], v[152:155], v[168:171], v[56:59]
	v_mfma_f32_16x16x32_bf16 v[72:75], v[156:159], v[168:171], v[72:75]
	v_mfma_f32_16x16x32_bf16 v[88:91], v[160:163], v[168:171], v[88:91]
	v_mfma_f32_16x16x32_bf16 v[12:15], v[140:143], v[172:175], v[12:15]
	v_mfma_f32_16x16x32_bf16 v[28:31], v[144:147], v[172:175], v[28:31]
	v_mfma_f32_16x16x32_bf16 v[44:47], v[148:151], v[172:175], v[44:47]
	v_mfma_f32_16x16x32_bf16 v[60:63], v[152:155], v[172:175], v[60:63]
	v_mfma_f32_16x16x32_bf16 v[76:79], v[156:159], v[172:175], v[76:79]
	v_mfma_f32_16x16x32_bf16 v[92:95], v[160:163], v[172:175], v[92:95]
	v_mfma_f32_16x16x32_bf16 v[16:19], v[140:143], v[176:179], v[16:19]
	v_mfma_f32_16x16x32_bf16 v[32:35], v[144:147], v[176:179], v[32:35]
	v_mfma_f32_16x16x32_bf16 v[48:51], v[148:151], v[176:179], v[48:51]
	v_mfma_f32_16x16x32_bf16 v[64:67], v[152:155], v[176:179], v[64:67]
	v_mfma_f32_16x16x32_bf16 v[80:83], v[156:159], v[176:179], v[80:83]
	v_mfma_f32_16x16x32_bf16 v[96:99], v[160:163], v[176:179], v[96:99]
	s_and_b32 s6, s35, 31
	s_mul_i32 s6, s6, 192
	s_lshr_b32 s7, s35, 5
	s_lshl_b32 s7, s7, 7
	s_nop 7
	s_mul_i32 s4, s6, 0x1000
	s_lshl_b32 s5, s7, 2
	s_add_u32 s4, s4, s5
	v_add_u32_e32 v197, s4, v205
	v_add_u32_e32 v192, s6, v190
	v_lshl_add_u32 v193, s7, 2, v191
	s_sub_i32 s4, s6, 0xc00
	s_max_i32 s4, s4, 0
	s_lshr_b32 s4, s4, 10
	s_add_i32 s5, s6, -2881
	s_max_i32 s5, s5, 0
	s_lshr_b32 s5, s5, 10
	s_movk_i32 s7, 0x1400
	s_cmp_eq_u32 s4, 0
	s_cselect_b32 s7, 0x1000, s7
	s_mul_i32 s4, s4, 0x6000
	s_mul_i32 s5, s5, 0x6000
	v_mov_b32_e32 v194, v197
	v_add_u32_e32 v195, 0, v192
	v_cmp_gt_u32_e32 vcc, 0x1000, v195
	v_mov_b32_e32 v0, s98
	v_mov_b32_e32 v1, s99
	v_mov_b32_e32 v3, s58
	v_cndmask_b32_e32 v0, v0, v3, vcc
	v_mov_b32_e32 v3, s59
	v_cndmask_b32_e32 v1, v1, v3, vcc
	v_add_co_u32_e32 v0, vcc, v0, v194
	s_nop 1
	v_addc_co_u32_e32 v1, vcc, 0, v1, vcc
	global_load_dwordx4 v[100:103], v[0:1], off
	v_add_u32_e32 v194, 0x4000, v194
	v_add_u32_e32 v195, 4, v192
	v_cmp_gt_u32_e32 vcc, 0x1000, v195
	v_mov_b32_e32 v0, s98
	v_mov_b32_e32 v1, s99
	v_mov_b32_e32 v3, s58
	v_cndmask_b32_e32 v0, v0, v3, vcc
	v_mov_b32_e32 v3, s59
	v_cndmask_b32_e32 v1, v1, v3, vcc
	v_add_co_u32_e32 v0, vcc, v0, v194
	s_nop 1
	v_addc_co_u32_e32 v1, vcc, 0, v1, vcc
	global_load_dwordx4 v[104:107], v[0:1], off
	v_add_u32_e32 v194, 0x4000, v194
	v_add_u32_e32 v195, 8, v192
	v_cmp_gt_u32_e32 vcc, 0x1000, v195
	v_mov_b32_e32 v0, s98
	v_mov_b32_e32 v1, s99
	v_mov_b32_e32 v3, s58
	v_cndmask_b32_e32 v0, v0, v3, vcc
	v_mov_b32_e32 v3, s59
	v_cndmask_b32_e32 v1, v1, v3, vcc
	v_add_co_u32_e32 v0, vcc, v0, v194
	s_nop 1
	v_addc_co_u32_e32 v1, vcc, 0, v1, vcc
	global_load_dwordx4 v[108:111], v[0:1], off
	v_add_u32_e32 v194, 0x4000, v194
	v_add_u32_e32 v195, 12, v192
	v_cmp_gt_u32_e32 vcc, 0x1000, v195
	v_mov_b32_e32 v0, s98
	v_mov_b32_e32 v1, s99
	v_mov_b32_e32 v3, s58
	v_cndmask_b32_e32 v0, v0, v3, vcc
	v_mov_b32_e32 v3, s59
	v_cndmask_b32_e32 v1, v1, v3, vcc
	v_add_co_u32_e32 v0, vcc, v0, v194
	s_nop 1
	v_addc_co_u32_e32 v1, vcc, 0, v1, vcc
	global_load_dwordx4 v[112:115], v[0:1], off
	v_add_u32_e32 v194, 0x4000, v194
	v_add_u32_e32 v195, 16, v192
	v_cmp_gt_u32_e32 vcc, 0x1000, v195
	v_mov_b32_e32 v0, s98
	v_mov_b32_e32 v1, s99
	v_mov_b32_e32 v3, s58
	v_cndmask_b32_e32 v0, v0, v3, vcc
	v_mov_b32_e32 v3, s59
	v_cndmask_b32_e32 v1, v1, v3, vcc
	v_add_co_u32_e32 v0, vcc, v0, v194
	s_nop 1
	v_addc_co_u32_e32 v1, vcc, 0, v1, vcc
	global_load_dwordx4 v[116:119], v[0:1], off
	v_add_u32_e32 v194, 0x4000, v194
	v_add_u32_e32 v195, 20, v192
	v_cmp_gt_u32_e32 vcc, 0x1000, v195
	v_mov_b32_e32 v0, s98
	v_mov_b32_e32 v1, s99
	v_mov_b32_e32 v3, s58
	v_cndmask_b32_e32 v0, v0, v3, vcc
	v_mov_b32_e32 v3, s59
	v_cndmask_b32_e32 v1, v1, v3, vcc
	v_add_co_u32_e32 v0, vcc, v0, v194
	s_nop 1
	v_addc_co_u32_e32 v1, vcc, 0, v1, vcc
	global_load_dwordx4 v[120:123], v[0:1], off
	v_add_u32_e32 v194, 0x4000, v194
	v_add_u32_e32 v195, 24, v192
	v_cmp_gt_u32_e32 vcc, 0x1000, v195
	v_mov_b32_e32 v0, s98
	v_mov_b32_e32 v1, s99
	v_mov_b32_e32 v3, s58
	v_cndmask_b32_e32 v0, v0, v3, vcc
	v_mov_b32_e32 v3, s59
	v_cndmask_b32_e32 v1, v1, v3, vcc
	v_add_co_u32_e32 v0, vcc, v0, v194
	s_nop 1
	v_addc_co_u32_e32 v1, vcc, 0, v1, vcc
	global_load_dwordx4 v[124:127], v[0:1], off
	v_add_u32_e32 v194, 0x4000, v194
	v_add_u32_e32 v195, 28, v192
	v_cmp_gt_u32_e32 vcc, 0x1000, v195
	v_mov_b32_e32 v0, s98
	v_mov_b32_e32 v1, s99
	v_mov_b32_e32 v3, s58
	v_cndmask_b32_e32 v0, v0, v3, vcc
	v_mov_b32_e32 v3, s59
	v_cndmask_b32_e32 v1, v1, v3, vcc
	v_add_co_u32_e32 v0, vcc, v0, v194
	s_nop 1
	v_addc_co_u32_e32 v1, vcc, 0, v1, vcc
	global_load_dwordx4 v[128:131], v[0:1], off
	v_add_u32_e32 v194, 0x4000, v194
	v_add_u32_e32 v195, 32, v192
	v_cmp_gt_u32_e32 vcc, 0x1000, v195
	v_mov_b32_e32 v0, s98
	v_mov_b32_e32 v1, s99
	v_mov_b32_e32 v3, s58
	v_cndmask_b32_e32 v0, v0, v3, vcc
	v_mov_b32_e32 v3, s59
	v_cndmask_b32_e32 v1, v1, v3, vcc
	v_add_co_u32_e32 v0, vcc, v0, v194
	s_nop 1
	v_addc_co_u32_e32 v1, vcc, 0, v1, vcc
	global_load_dwordx4 v[132:135], v[0:1], off
	v_add_u32_e32 v194, 0x4000, v194
	v_add_u32_e32 v195, 36, v192
	v_cmp_gt_u32_e32 vcc, 0x1000, v195
	v_mov_b32_e32 v0, s98
	v_mov_b32_e32 v1, s99
	v_mov_b32_e32 v3, s58
	v_cndmask_b32_e32 v0, v0, v3, vcc
	v_mov_b32_e32 v3, s59
	v_cndmask_b32_e32 v1, v1, v3, vcc
	v_add_co_u32_e32 v0, vcc, v0, v194
	s_nop 1
	v_addc_co_u32_e32 v1, vcc, 0, v1, vcc
	global_load_dwordx4 v[136:139], v[0:1], off
	v_add_u32_e32 v194, 0x4000, v194
	v_add_u32_e32 v195, 40, v192
	v_cmp_gt_u32_e32 vcc, 0x1000, v195
	v_mov_b32_e32 v0, s98
	v_mov_b32_e32 v1, s99
	v_mov_b32_e32 v3, s58
	v_cndmask_b32_e32 v0, v0, v3, vcc
	v_mov_b32_e32 v3, s59
	v_cndmask_b32_e32 v1, v1, v3, vcc
	v_add_co_u32_e32 v0, vcc, v0, v194
	s_nop 1
	v_addc_co_u32_e32 v1, vcc, 0, v1, vcc
	global_load_dwordx4 v[140:143], v[0:1], off
	v_add_u32_e32 v194, 0x4000, v194
	v_add_u32_e32 v195, 44, v192
	v_cmp_gt_u32_e32 vcc, 0x1000, v195
	v_mov_b32_e32 v0, s98
	v_mov_b32_e32 v1, s99
	v_mov_b32_e32 v3, s58
	v_cndmask_b32_e32 v0, v0, v3, vcc
	v_mov_b32_e32 v3, s59
	v_cndmask_b32_e32 v1, v1, v3, vcc
	v_add_co_u32_e32 v0, vcc, v0, v194
	s_nop 1
	v_addc_co_u32_e32 v1, vcc, 0, v1, vcc
	global_load_dwordx4 v[144:147], v[0:1], off
	v_add_u32_e32 v194, 0x4000, v194
	v_add_u32_e32 v195, s4, v193
	global_load_dwordx4 v[148:151], v195, s[100:101]
	v_add_u32_e32 v195, s5, v193
	global_load_dwordx4 v[152:155], v195, s[100:101]
	ds_write_b32 v203, v4 offset:0
	ds_write_b32 v203, v5 offset:272
	ds_write_b32 v203, v6 offset:544
	ds_write_b32 v203, v7 offset:816
	ds_write_b32 v203, v8 offset:64
	ds_write_b32 v203, v9 offset:336
	ds_write_b32 v203, v10 offset:608
	ds_write_b32 v203, v11 offset:880
	ds_write_b32 v203, v12 offset:128
	ds_write_b32 v203, v13 offset:400
	ds_write_b32 v203, v14 offset:672
	ds_write_b32 v203, v15 offset:944
	ds_write_b32 v203, v16 offset:192
	ds_write_b32 v203, v17 offset:464
	ds_write_b32 v203, v18 offset:736
	ds_write_b32 v203, v19 offset:1008
	s_waitcnt lgkmcnt(0)
	ds_read_b128 v[156:159], v204 offset:0
	ds_read_b128 v[160:163], v204 offset:1088
	ds_read_b128 v[164:167], v204 offset:2176
	ds_read_b128 v[168:171], v204 offset:3264
	s_waitcnt lgkmcnt(0)
	v_add_u32_e32 v195, 48, v192
	v_cmp_gt_u32_e32 vcc, 0x1000, v195
	v_mov_b32_e32 v0, s98
	v_mov_b32_e32 v1, s99
	v_mov_b32_e32 v3, s58
	v_cndmask_b32_e32 v0, v0, v3, vcc
	v_mov_b32_e32 v3, s59
	v_cndmask_b32_e32 v1, v1, v3, vcc
	v_add_co_u32_e32 v0, vcc, v0, v194
	s_nop 1
	v_addc_co_u32_e32 v1, vcc, 0, v1, vcc
	global_load_dwordx4 v[4:7], v[0:1], off
	v_add_u32_e32 v194, 0x4000, v194
	v_add_u32_e32 v195, 52, v192
	v_cmp_gt_u32_e32 vcc, 0x1000, v195
	v_mov_b32_e32 v0, s98
	v_mov_b32_e32 v1, s99
	v_mov_b32_e32 v3, s58
	v_cndmask_b32_e32 v0, v0, v3, vcc
	v_mov_b32_e32 v3, s59
	v_cndmask_b32_e32 v1, v1, v3, vcc
	v_add_co_u32_e32 v0, vcc, v0, v194
	s_nop 1
	v_addc_co_u32_e32 v1, vcc, 0, v1, vcc
	global_load_dwordx4 v[8:11], v[0:1], off
	v_add_u32_e32 v194, 0x4000, v194
	v_add_u32_e32 v195, 56, v192
	v_cmp_gt_u32_e32 vcc, 0x1000, v195
	v_mov_b32_e32 v0, s98
	v_mov_b32_e32 v1, s99
	v_mov_b32_e32 v3, s58
	v_cndmask_b32_e32 v0, v0, v3, vcc
	v_mov_b32_e32 v3, s59
	v_cndmask_b32_e32 v1, v1, v3, vcc
	v_add_co_u32_e32 v0, vcc, v0, v194
	s_nop 1
	v_addc_co_u32_e32 v1, vcc, 0, v1, vcc
	global_load_dwordx4 v[12:15], v[0:1], off
	v_add_u32_e32 v194, 0x4000, v194
	v_add_u32_e32 v195, 60, v192
	v_cmp_gt_u32_e32 vcc, 0x1000, v195
	v_mov_b32_e32 v0, s98
	v_mov_b32_e32 v1, s99
	v_mov_b32_e32 v3, s58
	v_cndmask_b32_e32 v0, v0, v3, vcc
	v_mov_b32_e32 v3, s59
	v_cndmask_b32_e32 v1, v1, v3, vcc
	v_add_co_u32_e32 v0, vcc, v0, v194
	s_nop 1
	v_addc_co_u32_e32 v1, vcc, 0, v1, vcc
	global_load_dwordx4 v[16:19], v[0:1], off
	v_add_u32_e32 v194, 0x4000, v194
	v_add_u32_e32 v195, 0, v192
	v_cmp_le_u32_e32 vcc, s7, v195
	s_waitcnt vmcnt(4)
	v_cndmask_b32_e32 v172, v148, v152, vcc
	v_cndmask_b32_e32 v173, v149, v153, vcc
	v_cndmask_b32_e32 v174, v150, v154, vcc
	v_cndmask_b32_e32 v175, v151, v155, vcc
	v_fmac_f32_e32 v100, v172, v156
	v_fmac_f32_e32 v101, v173, v157
	v_fmac_f32_e32 v102, v174, v158
	v_fmac_f32_e32 v103, v175, v159
	global_store_dwordx4 v197, v[100:103], s[56:57] sc0 sc1
	v_add_u32_e32 v197, 0x4000, v197
	v_add_u32_e32 v195, 4, v192
	v_cmp_le_u32_e32 vcc, s7, v195
	s_waitcnt vmcnt(5)
	s_waitcnt lgkmcnt(2)
	v_cndmask_b32_e32 v172, v148, v152, vcc
	v_cndmask_b32_e32 v173, v149, v153, vcc
	v_cndmask_b32_e32 v174, v150, v154, vcc
	v_cndmask_b32_e32 v175, v151, v155, vcc
	v_fmac_f32_e32 v104, v172, v160
	v_fmac_f32_e32 v105, v173, v161
	v_fmac_f32_e32 v106, v174, v162
	v_fmac_f32_e32 v107, v175, v163
	global_store_dwordx4 v197, v[104:107], s[56:57] sc0 sc1
	v_add_u32_e32 v197, 0x4000, v197
	v_add_u32_e32 v195, 8, v192
	v_cmp_le_u32_e32 vcc, s7, v195
	s_waitcnt vmcnt(6)
	s_waitcnt lgkmcnt(1)
	v_cndmask_b32_e32 v172, v148, v152, vcc
	v_cndmask_b32_e32 v173, v149, v153, vcc
	v_cndmask_b32_e32 v174, v150, v154, vcc
	v_cndmask_b32_e32 v175, v151, v155, vcc
	v_fmac_f32_e32 v108, v172, v164
	v_fmac_f32_e32 v109, v173, v165
	v_fmac_f32_e32 v110, v174, v166
	v_fmac_f32_e32 v111, v175, v167
	global_store_dwordx4 v197, v[108:111], s[56:57] sc0 sc1
	v_add_u32_e32 v197, 0x4000, v197
	v_add_u32_e32 v195, 12, v192
	v_cmp_le_u32_e32 vcc, s7, v195
	s_waitcnt vmcnt(7)
	s_waitcnt lgkmcnt(0)
	v_cndmask_b32_e32 v172, v148, v152, vcc
	v_cndmask_b32_e32 v173, v149, v153, vcc
	v_cndmask_b32_e32 v174, v150, v154, vcc
	v_cndmask_b32_e32 v175, v151, v155, vcc
	v_fmac_f32_e32 v112, v172, v168
	v_fmac_f32_e32 v113, v173, v169
	v_fmac_f32_e32 v114, v174, v170
	v_fmac_f32_e32 v115, v175, v171
	global_store_dwordx4 v197, v[112:115], s[56:57] sc0 sc1
	v_add_u32_e32 v197, 0x4000, v197
	ds_write_b32 v203, v20 offset:0
	ds_write_b32 v203, v21 offset:272
	ds_write_b32 v203, v22 offset:544
	ds_write_b32 v203, v23 offset:816
	ds_write_b32 v203, v24 offset:64
	ds_write_b32 v203, v25 offset:336
	ds_write_b32 v203, v26 offset:608
	ds_write_b32 v203, v27 offset:880
	ds_write_b32 v203, v28 offset:128
	ds_write_b32 v203, v29 offset:400
	ds_write_b32 v203, v30 offset:672
	ds_write_b32 v203, v31 offset:944
	ds_write_b32 v203, v32 offset:192
	ds_write_b32 v203, v33 offset:464
	ds_write_b32 v203, v34 offset:736
	ds_write_b32 v203, v35 offset:1008
	s_waitcnt lgkmcnt(0)
	ds_read_b128 v[156:159], v204 offset:0
	ds_read_b128 v[160:163], v204 offset:1088
	ds_read_b128 v[164:167], v204 offset:2176
	ds_read_b128 v[168:171], v204 offset:3264
	s_waitcnt lgkmcnt(0)
	v_add_u32_e32 v195, 64, v192
	v_cmp_gt_u32_e32 vcc, 0x1000, v195
	v_mov_b32_e32 v0, s98
	v_mov_b32_e32 v1, s99
	v_mov_b32_e32 v3, s58
	v_cndmask_b32_e32 v0, v0, v3, vcc
	v_mov_b32_e32 v3, s59
	v_cndmask_b32_e32 v1, v1, v3, vcc
	v_add_co_u32_e32 v0, vcc, v0, v194
	s_nop 1
	v_addc_co_u32_e32 v1, vcc, 0, v1, vcc
	global_load_dwordx4 v[20:23], v[0:1], off
	v_add_u32_e32 v194, 0x4000, v194
	v_add_u32_e32 v195, 68, v192
	v_cmp_gt_u32_e32 vcc, 0x1000, v195
	v_mov_b32_e32 v0, s98
	v_mov_b32_e32 v1, s99
	v_mov_b32_e32 v3, s58
	v_cndmask_b32_e32 v0, v0, v3, vcc
	v_mov_b32_e32 v3, s59
	v_cndmask_b32_e32 v1, v1, v3, vcc
	v_add_co_u32_e32 v0, vcc, v0, v194
	s_nop 1
	v_addc_co_u32_e32 v1, vcc, 0, v1, vcc
	global_load_dwordx4 v[24:27], v[0:1], off
	v_add_u32_e32 v194, 0x4000, v194
	v_add_u32_e32 v195, 72, v192
	v_cmp_gt_u32_e32 vcc, 0x1000, v195
	v_mov_b32_e32 v0, s98
	v_mov_b32_e32 v1, s99
	v_mov_b32_e32 v3, s58
	v_cndmask_b32_e32 v0, v0, v3, vcc
	v_mov_b32_e32 v3, s59
	v_cndmask_b32_e32 v1, v1, v3, vcc
	v_add_co_u32_e32 v0, vcc, v0, v194
	s_nop 1
	v_addc_co_u32_e32 v1, vcc, 0, v1, vcc
	global_load_dwordx4 v[28:31], v[0:1], off
	v_add_u32_e32 v194, 0x4000, v194
	v_add_u32_e32 v195, 76, v192
	v_cmp_gt_u32_e32 vcc, 0x1000, v195
	v_mov_b32_e32 v0, s98
	v_mov_b32_e32 v1, s99
	v_mov_b32_e32 v3, s58
	v_cndmask_b32_e32 v0, v0, v3, vcc
	v_mov_b32_e32 v3, s59
	v_cndmask_b32_e32 v1, v1, v3, vcc
	v_add_co_u32_e32 v0, vcc, v0, v194
	s_nop 1
	v_addc_co_u32_e32 v1, vcc, 0, v1, vcc
	global_load_dwordx4 v[32:35], v[0:1], off
	v_add_u32_e32 v194, 0x4000, v194
	v_add_u32_e32 v195, 16, v192
	v_cmp_le_u32_e32 vcc, s7, v195
	s_waitcnt vmcnt(12)
	v_cndmask_b32_e32 v172, v148, v152, vcc
	v_cndmask_b32_e32 v173, v149, v153, vcc
	v_cndmask_b32_e32 v174, v150, v154, vcc
	v_cndmask_b32_e32 v175, v151, v155, vcc
	v_fmac_f32_e32 v116, v172, v156
	v_fmac_f32_e32 v117, v173, v157
	v_fmac_f32_e32 v118, v174, v158
	v_fmac_f32_e32 v119, v175, v159
	global_store_dwordx4 v197, v[116:119], s[56:57] sc0 sc1
	v_add_u32_e32 v197, 0x4000, v197
	v_add_u32_e32 v195, 20, v192
	v_cmp_le_u32_e32 vcc, s7, v195
	s_waitcnt vmcnt(13)
	s_waitcnt lgkmcnt(2)
	v_cndmask_b32_e32 v172, v148, v152, vcc
	v_cndmask_b32_e32 v173, v149, v153, vcc
	v_cndmask_b32_e32 v174, v150, v154, vcc
	v_cndmask_b32_e32 v175, v151, v155, vcc
	v_fmac_f32_e32 v120, v172, v160
	v_fmac_f32_e32 v121, v173, v161
	v_fmac_f32_e32 v122, v174, v162
	v_fmac_f32_e32 v123, v175, v163
	global_store_dwordx4 v197, v[120:123], s[56:57] sc0 sc1
	v_add_u32_e32 v197, 0x4000, v197
	v_add_u32_e32 v195, 24, v192
	v_cmp_le_u32_e32 vcc, s7, v195
	s_waitcnt vmcnt(14)
	s_waitcnt lgkmcnt(1)
	v_cndmask_b32_e32 v172, v148, v152, vcc
	v_cndmask_b32_e32 v173, v149, v153, vcc
	v_cndmask_b32_e32 v174, v150, v154, vcc
	v_cndmask_b32_e32 v175, v151, v155, vcc
	v_fmac_f32_e32 v124, v172, v164
	v_fmac_f32_e32 v125, v173, v165
	v_fmac_f32_e32 v126, v174, v166
	v_fmac_f32_e32 v127, v175, v167
	global_store_dwordx4 v197, v[124:127], s[56:57] sc0 sc1
	v_add_u32_e32 v197, 0x4000, v197
	v_add_u32_e32 v195, 28, v192
	v_cmp_le_u32_e32 vcc, s7, v195
	s_waitcnt vmcnt(15)
	s_waitcnt lgkmcnt(0)
	v_cndmask_b32_e32 v172, v148, v152, vcc
	v_cndmask_b32_e32 v173, v149, v153, vcc
	v_cndmask_b32_e32 v174, v150, v154, vcc
	v_cndmask_b32_e32 v175, v151, v155, vcc
	v_fmac_f32_e32 v128, v172, v168
	v_fmac_f32_e32 v129, v173, v169
	v_fmac_f32_e32 v130, v174, v170
	v_fmac_f32_e32 v131, v175, v171
	global_store_dwordx4 v197, v[128:131], s[56:57] sc0 sc1
	v_add_u32_e32 v197, 0x4000, v197
	ds_write_b32 v203, v36 offset:0
	ds_write_b32 v203, v37 offset:272
	ds_write_b32 v203, v38 offset:544
	ds_write_b32 v203, v39 offset:816
	ds_write_b32 v203, v40 offset:64
	ds_write_b32 v203, v41 offset:336
	ds_write_b32 v203, v42 offset:608
	ds_write_b32 v203, v43 offset:880
	ds_write_b32 v203, v44 offset:128
	ds_write_b32 v203, v45 offset:400
	ds_write_b32 v203, v46 offset:672
	ds_write_b32 v203, v47 offset:944
	ds_write_b32 v203, v48 offset:192
	ds_write_b32 v203, v49 offset:464
	ds_write_b32 v203, v50 offset:736
	ds_write_b32 v203, v51 offset:1008
	s_waitcnt lgkmcnt(0)
	ds_read_b128 v[156:159], v204 offset:0
	ds_read_b128 v[160:163], v204 offset:1088
	ds_read_b128 v[164:167], v204 offset:2176
	ds_read_b128 v[168:171], v204 offset:3264
	s_waitcnt lgkmcnt(0)
	v_add_u32_e32 v195, 80, v192
	v_cmp_gt_u32_e32 vcc, 0x1000, v195
	v_mov_b32_e32 v0, s98
	v_mov_b32_e32 v1, s99
	v_mov_b32_e32 v3, s58
	v_cndmask_b32_e32 v0, v0, v3, vcc
	v_mov_b32_e32 v3, s59
	v_cndmask_b32_e32 v1, v1, v3, vcc
	v_add_co_u32_e32 v0, vcc, v0, v194
	s_nop 1
	v_addc_co_u32_e32 v1, vcc, 0, v1, vcc
	global_load_dwordx4 v[36:39], v[0:1], off
	v_add_u32_e32 v194, 0x4000, v194
	v_add_u32_e32 v195, 84, v192
	v_cmp_gt_u32_e32 vcc, 0x1000, v195
	v_mov_b32_e32 v0, s98
	v_mov_b32_e32 v1, s99
	v_mov_b32_e32 v3, s58
	v_cndmask_b32_e32 v0, v0, v3, vcc
	v_mov_b32_e32 v3, s59
	v_cndmask_b32_e32 v1, v1, v3, vcc
	v_add_co_u32_e32 v0, vcc, v0, v194
	s_nop 1
	v_addc_co_u32_e32 v1, vcc, 0, v1, vcc
	global_load_dwordx4 v[40:43], v[0:1], off
	v_add_u32_e32 v194, 0x4000, v194
	v_add_u32_e32 v195, 88, v192
	v_cmp_gt_u32_e32 vcc, 0x1000, v195
	v_mov_b32_e32 v0, s98
	v_mov_b32_e32 v1, s99
	v_mov_b32_e32 v3, s58
	v_cndmask_b32_e32 v0, v0, v3, vcc
	v_mov_b32_e32 v3, s59
	v_cndmask_b32_e32 v1, v1, v3, vcc
	v_add_co_u32_e32 v0, vcc, v0, v194
	s_nop 1
	v_addc_co_u32_e32 v1, vcc, 0, v1, vcc
	global_load_dwordx4 v[44:47], v[0:1], off
	v_add_u32_e32 v194, 0x4000, v194
	v_add_u32_e32 v195, 92, v192
	v_cmp_gt_u32_e32 vcc, 0x1000, v195
	v_mov_b32_e32 v0, s98
	v_mov_b32_e32 v1, s99
	v_mov_b32_e32 v3, s58
	v_cndmask_b32_e32 v0, v0, v3, vcc
	v_mov_b32_e32 v3, s59
	v_cndmask_b32_e32 v1, v1, v3, vcc
	v_add_co_u32_e32 v0, vcc, v0, v194
	s_nop 1
	v_addc_co_u32_e32 v1, vcc, 0, v1, vcc
	global_load_dwordx4 v[48:51], v[0:1], off
	v_add_u32_e32 v194, 0x4000, v194
	v_add_u32_e32 v195, 32, v192
	v_cmp_le_u32_e32 vcc, s7, v195
	s_waitcnt vmcnt(20)
	v_cndmask_b32_e32 v172, v148, v152, vcc
	v_cndmask_b32_e32 v173, v149, v153, vcc
	v_cndmask_b32_e32 v174, v150, v154, vcc
	v_cndmask_b32_e32 v175, v151, v155, vcc
	v_fmac_f32_e32 v132, v172, v156
	v_fmac_f32_e32 v133, v173, v157
	v_fmac_f32_e32 v134, v174, v158
	v_fmac_f32_e32 v135, v175, v159
	global_store_dwordx4 v197, v[132:135], s[56:57] sc0 sc1
	v_add_u32_e32 v197, 0x4000, v197
	v_add_u32_e32 v195, 36, v192
	v_cmp_le_u32_e32 vcc, s7, v195
	s_waitcnt vmcnt(21)
	s_waitcnt lgkmcnt(2)
	v_cndmask_b32_e32 v172, v148, v152, vcc
	v_cndmask_b32_e32 v173, v149, v153, vcc
	v_cndmask_b32_e32 v174, v150, v154, vcc
	v_cndmask_b32_e32 v175, v151, v155, vcc
	v_fmac_f32_e32 v136, v172, v160
	v_fmac_f32_e32 v137, v173, v161
	v_fmac_f32_e32 v138, v174, v162
	v_fmac_f32_e32 v139, v175, v163
	global_store_dwordx4 v197, v[136:139], s[56:57] sc0 sc1
	v_add_u32_e32 v197, 0x4000, v197
	v_add_u32_e32 v195, 40, v192
	v_cmp_le_u32_e32 vcc, s7, v195
	s_waitcnt vmcnt(22)
	s_waitcnt lgkmcnt(1)
	v_cndmask_b32_e32 v172, v148, v152, vcc
	v_cndmask_b32_e32 v173, v149, v153, vcc
	v_cndmask_b32_e32 v174, v150, v154, vcc
	v_cndmask_b32_e32 v175, v151, v155, vcc
	v_fmac_f32_e32 v140, v172, v164
	v_fmac_f32_e32 v141, v173, v165
	v_fmac_f32_e32 v142, v174, v166
	v_fmac_f32_e32 v143, v175, v167
	global_store_dwordx4 v197, v[140:143], s[56:57] sc0 sc1
	v_add_u32_e32 v197, 0x4000, v197
	v_add_u32_e32 v195, 44, v192
	v_cmp_le_u32_e32 vcc, s7, v195
	s_waitcnt vmcnt(23)
	s_waitcnt lgkmcnt(0)
	v_cndmask_b32_e32 v172, v148, v152, vcc
	v_cndmask_b32_e32 v173, v149, v153, vcc
	v_cndmask_b32_e32 v174, v150, v154, vcc
	v_cndmask_b32_e32 v175, v151, v155, vcc
	v_fmac_f32_e32 v144, v172, v168
	v_fmac_f32_e32 v145, v173, v169
	v_fmac_f32_e32 v146, v174, v170
	v_fmac_f32_e32 v147, v175, v171
	global_store_dwordx4 v197, v[144:147], s[56:57] sc0 sc1
	v_add_u32_e32 v197, 0x4000, v197
	ds_write_b32 v203, v52 offset:0
	ds_write_b32 v203, v53 offset:272
	ds_write_b32 v203, v54 offset:544
	ds_write_b32 v203, v55 offset:816
	ds_write_b32 v203, v56 offset:64
	ds_write_b32 v203, v57 offset:336
	ds_write_b32 v203, v58 offset:608
	ds_write_b32 v203, v59 offset:880
	ds_write_b32 v203, v60 offset:128
	ds_write_b32 v203, v61 offset:400
	ds_write_b32 v203, v62 offset:672
	ds_write_b32 v203, v63 offset:944
	ds_write_b32 v203, v64 offset:192
	ds_write_b32 v203, v65 offset:464
	ds_write_b32 v203, v66 offset:736
	ds_write_b32 v203, v67 offset:1008
	s_waitcnt lgkmcnt(0)
	ds_read_b128 v[156:159], v204 offset:0
	ds_read_b128 v[160:163], v204 offset:1088
	ds_read_b128 v[164:167], v204 offset:2176
	ds_read_b128 v[168:171], v204 offset:3264
	v_add_u32_e32 v195, 48, v192
	v_cmp_le_u32_e32 vcc, s7, v195
	s_waitcnt vmcnt(23)
	s_waitcnt lgkmcnt(3)
	v_cndmask_b32_e32 v172, v148, v152, vcc
	v_cndmask_b32_e32 v173, v149, v153, vcc
	v_cndmask_b32_e32 v174, v150, v154, vcc
	v_cndmask_b32_e32 v175, v151, v155, vcc
	v_fmac_f32_e32 v4, v172, v156
	v_fmac_f32_e32 v5, v173, v157
	v_fmac_f32_e32 v6, v174, v158
	v_fmac_f32_e32 v7, v175, v159
	global_store_dwordx4 v197, v[4:7], s[56:57] sc0 sc1
	v_add_u32_e32 v197, 0x4000, v197
	v_add_u32_e32 v195, 52, v192
	v_cmp_le_u32_e32 vcc, s7, v195
	s_waitcnt vmcnt(23)
	s_waitcnt lgkmcnt(2)
	v_cndmask_b32_e32 v172, v148, v152, vcc
	v_cndmask_b32_e32 v173, v149, v153, vcc
	v_cndmask_b32_e32 v174, v150, v154, vcc
	v_cndmask_b32_e32 v175, v151, v155, vcc
	v_fmac_f32_e32 v8, v172, v160
	v_fmac_f32_e32 v9, v173, v161
	v_fmac_f32_e32 v10, v174, v162
	v_fmac_f32_e32 v11, v175, v163
	global_store_dwordx4 v197, v[8:11], s[56:57] sc0 sc1
	v_add_u32_e32 v197, 0x4000, v197
	v_add_u32_e32 v195, 56, v192
	v_cmp_le_u32_e32 vcc, s7, v195
	s_waitcnt vmcnt(23)
	s_waitcnt lgkmcnt(1)
	v_cndmask_b32_e32 v172, v148, v152, vcc
	v_cndmask_b32_e32 v173, v149, v153, vcc
	v_cndmask_b32_e32 v174, v150, v154, vcc
	v_cndmask_b32_e32 v175, v151, v155, vcc
	v_fmac_f32_e32 v12, v172, v164
	v_fmac_f32_e32 v13, v173, v165
	v_fmac_f32_e32 v14, v174, v166
	v_fmac_f32_e32 v15, v175, v167
	global_store_dwordx4 v197, v[12:15], s[56:57] sc0 sc1
	v_add_u32_e32 v197, 0x4000, v197
	v_add_u32_e32 v195, 60, v192
	v_cmp_le_u32_e32 vcc, s7, v195
	s_waitcnt vmcnt(23)
	s_waitcnt lgkmcnt(0)
	v_cndmask_b32_e32 v172, v148, v152, vcc
	v_cndmask_b32_e32 v173, v149, v153, vcc
	v_cndmask_b32_e32 v174, v150, v154, vcc
	v_cndmask_b32_e32 v175, v151, v155, vcc
	v_fmac_f32_e32 v16, v172, v168
	v_fmac_f32_e32 v17, v173, v169
	v_fmac_f32_e32 v18, v174, v170
	v_fmac_f32_e32 v19, v175, v171
	global_store_dwordx4 v197, v[16:19], s[56:57] sc0 sc1
	v_add_u32_e32 v197, 0x4000, v197
	ds_write_b32 v203, v68 offset:0
	ds_write_b32 v203, v69 offset:272
	ds_write_b32 v203, v70 offset:544
	ds_write_b32 v203, v71 offset:816
	ds_write_b32 v203, v72 offset:64
	ds_write_b32 v203, v73 offset:336
	ds_write_b32 v203, v74 offset:608
	ds_write_b32 v203, v75 offset:880
	ds_write_b32 v203, v76 offset:128
	ds_write_b32 v203, v77 offset:400
	ds_write_b32 v203, v78 offset:672
	ds_write_b32 v203, v79 offset:944
	ds_write_b32 v203, v80 offset:192
	ds_write_b32 v203, v81 offset:464
	ds_write_b32 v203, v82 offset:736
	ds_write_b32 v203, v83 offset:1008
	s_waitcnt lgkmcnt(0)
	ds_read_b128 v[156:159], v204 offset:0
	ds_read_b128 v[160:163], v204 offset:1088
	ds_read_b128 v[164:167], v204 offset:2176
	ds_read_b128 v[168:171], v204 offset:3264
	v_add_u32_e32 v195, 64, v192
	v_cmp_le_u32_e32 vcc, s7, v195
	s_waitcnt vmcnt(19)
	s_waitcnt lgkmcnt(3)
	v_cndmask_b32_e32 v172, v148, v152, vcc
	v_cndmask_b32_e32 v173, v149, v153, vcc
	v_cndmask_b32_e32 v174, v150, v154, vcc
	v_cndmask_b32_e32 v175, v151, v155, vcc
	v_fmac_f32_e32 v20, v172, v156
	v_fmac_f32_e32 v21, v173, v157
	v_fmac_f32_e32 v22, v174, v158
	v_fmac_f32_e32 v23, v175, v159
	global_store_dwordx4 v197, v[20:23], s[56:57] sc0 sc1
	v_add_u32_e32 v197, 0x4000, v197
	v_add_u32_e32 v195, 68, v192
	v_cmp_le_u32_e32 vcc, s7, v195
	s_waitcnt vmcnt(19)
	s_waitcnt lgkmcnt(2)
	v_cndmask_b32_e32 v172, v148, v152, vcc
	v_cndmask_b32_e32 v173, v149, v153, vcc
	v_cndmask_b32_e32 v174, v150, v154, vcc
	v_cndmask_b32_e32 v175, v151, v155, vcc
	v_fmac_f32_e32 v24, v172, v160
	v_fmac_f32_e32 v25, v173, v161
	v_fmac_f32_e32 v26, v174, v162
	v_fmac_f32_e32 v27, v175, v163
	global_store_dwordx4 v197, v[24:27], s[56:57] sc0 sc1
	v_add_u32_e32 v197, 0x4000, v197
	v_add_u32_e32 v195, 72, v192
	v_cmp_le_u32_e32 vcc, s7, v195
	s_waitcnt vmcnt(19)
	s_waitcnt lgkmcnt(1)
	v_cndmask_b32_e32 v172, v148, v152, vcc
	v_cndmask_b32_e32 v173, v149, v153, vcc
	v_cndmask_b32_e32 v174, v150, v154, vcc
	v_cndmask_b32_e32 v175, v151, v155, vcc
	v_fmac_f32_e32 v28, v172, v164
	v_fmac_f32_e32 v29, v173, v165
	v_fmac_f32_e32 v30, v174, v166
	v_fmac_f32_e32 v31, v175, v167
	global_store_dwordx4 v197, v[28:31], s[56:57] sc0 sc1
	v_add_u32_e32 v197, 0x4000, v197
	v_add_u32_e32 v195, 76, v192
	v_cmp_le_u32_e32 vcc, s7, v195
	s_waitcnt vmcnt(19)
	s_waitcnt lgkmcnt(0)
	v_cndmask_b32_e32 v172, v148, v152, vcc
	v_cndmask_b32_e32 v173, v149, v153, vcc
	v_cndmask_b32_e32 v174, v150, v154, vcc
	v_cndmask_b32_e32 v175, v151, v155, vcc
	v_fmac_f32_e32 v32, v172, v168
	v_fmac_f32_e32 v33, v173, v169
	v_fmac_f32_e32 v34, v174, v170
	v_fmac_f32_e32 v35, v175, v171
	global_store_dwordx4 v197, v[32:35], s[56:57] sc0 sc1
	v_add_u32_e32 v197, 0x4000, v197
	ds_write_b32 v203, v84 offset:0
	ds_write_b32 v203, v85 offset:272
	ds_write_b32 v203, v86 offset:544
	ds_write_b32 v203, v87 offset:816
	ds_write_b32 v203, v88 offset:64
	ds_write_b32 v203, v89 offset:336
	ds_write_b32 v203, v90 offset:608
	ds_write_b32 v203, v91 offset:880
	ds_write_b32 v203, v92 offset:128
	ds_write_b32 v203, v93 offset:400
	ds_write_b32 v203, v94 offset:672
	ds_write_b32 v203, v95 offset:944
	ds_write_b32 v203, v96 offset:192
	ds_write_b32 v203, v97 offset:464
	ds_write_b32 v203, v98 offset:736
	ds_write_b32 v203, v99 offset:1008
	s_waitcnt lgkmcnt(0)
	ds_read_b128 v[156:159], v204 offset:0
	ds_read_b128 v[160:163], v204 offset:1088
	ds_read_b128 v[164:167], v204 offset:2176
	ds_read_b128 v[168:171], v204 offset:3264
	v_add_u32_e32 v195, 80, v192
	v_cmp_le_u32_e32 vcc, s7, v195
	s_waitcnt vmcnt(15)
	s_waitcnt lgkmcnt(3)
	v_cndmask_b32_e32 v172, v148, v152, vcc
	v_cndmask_b32_e32 v173, v149, v153, vcc
	v_cndmask_b32_e32 v174, v150, v154, vcc
	v_cndmask_b32_e32 v175, v151, v155, vcc
	v_fmac_f32_e32 v36, v172, v156
	v_fmac_f32_e32 v37, v173, v157
	v_fmac_f32_e32 v38, v174, v158
	v_fmac_f32_e32 v39, v175, v159
	global_store_dwordx4 v197, v[36:39], s[56:57] sc0 sc1
	v_add_u32_e32 v197, 0x4000, v197
	v_add_u32_e32 v195, 84, v192
	v_cmp_le_u32_e32 vcc, s7, v195
	s_waitcnt vmcnt(15)
	s_waitcnt lgkmcnt(2)
	v_cndmask_b32_e32 v172, v148, v152, vcc
	v_cndmask_b32_e32 v173, v149, v153, vcc
	v_cndmask_b32_e32 v174, v150, v154, vcc
	v_cndmask_b32_e32 v175, v151, v155, vcc
	v_fmac_f32_e32 v40, v172, v160
	v_fmac_f32_e32 v41, v173, v161
	v_fmac_f32_e32 v42, v174, v162
	v_fmac_f32_e32 v43, v175, v163
	global_store_dwordx4 v197, v[40:43], s[56:57] sc0 sc1
	v_add_u32_e32 v197, 0x4000, v197
	v_add_u32_e32 v195, 88, v192
	v_cmp_le_u32_e32 vcc, s7, v195
	s_waitcnt vmcnt(15)
	s_waitcnt lgkmcnt(1)
	v_cndmask_b32_e32 v172, v148, v152, vcc
	v_cndmask_b32_e32 v173, v149, v153, vcc
	v_cndmask_b32_e32 v174, v150, v154, vcc
	v_cndmask_b32_e32 v175, v151, v155, vcc
	v_fmac_f32_e32 v44, v172, v164
	v_fmac_f32_e32 v45, v173, v165
	v_fmac_f32_e32 v46, v174, v166
	v_fmac_f32_e32 v47, v175, v167
	global_store_dwordx4 v197, v[44:47], s[56:57] sc0 sc1
	v_add_u32_e32 v197, 0x4000, v197
	v_add_u32_e32 v195, 92, v192
	v_cmp_le_u32_e32 vcc, s7, v195
	s_waitcnt vmcnt(15)
	s_waitcnt lgkmcnt(0)
	v_cndmask_b32_e32 v172, v148, v152, vcc
	v_cndmask_b32_e32 v173, v149, v153, vcc
	v_cndmask_b32_e32 v174, v150, v154, vcc
	v_cndmask_b32_e32 v175, v151, v155, vcc
	v_fmac_f32_e32 v48, v172, v168
	v_fmac_f32_e32 v49, v173, v169
	v_fmac_f32_e32 v50, v174, v170
	v_fmac_f32_e32 v51, v175, v171
	global_store_dwordx4 v197, v[48:51], s[56:57] sc0 sc1
	v_add_u32_e32 v197, 0x4000, v197
	v_mov_b32_e32 v4, 0
	v_mov_b32_e32 v5, 0
	v_mov_b32_e32 v6, 0
	v_mov_b32_e32 v7, 0
	v_mov_b32_e32 v8, 0
	v_mov_b32_e32 v9, 0
	v_mov_b32_e32 v10, 0
	v_mov_b32_e32 v11, 0
	v_mov_b32_e32 v12, 0
	v_mov_b32_e32 v13, 0
	v_mov_b32_e32 v14, 0
	v_mov_b32_e32 v15, 0
	v_mov_b32_e32 v16, 0
	v_mov_b32_e32 v17, 0
	v_mov_b32_e32 v18, 0
	v_mov_b32_e32 v19, 0
	v_mov_b32_e32 v20, 0
	v_mov_b32_e32 v21, 0
	v_mov_b32_e32 v22, 0
	v_mov_b32_e32 v23, 0
	v_mov_b32_e32 v24, 0
	v_mov_b32_e32 v25, 0
	v_mov_b32_e32 v26, 0
	v_mov_b32_e32 v27, 0
	v_mov_b32_e32 v28, 0
	v_mov_b32_e32 v29, 0
	v_mov_b32_e32 v30, 0
	v_mov_b32_e32 v31, 0
	v_mov_b32_e32 v32, 0
	v_mov_b32_e32 v33, 0
	v_mov_b32_e32 v34, 0
	v_mov_b32_e32 v35, 0
	v_mov_b32_e32 v36, 0
	v_mov_b32_e32 v37, 0
	v_mov_b32_e32 v38, 0
	v_mov_b32_e32 v39, 0
	v_mov_b32_e32 v40, 0
	v_mov_b32_e32 v41, 0
	v_mov_b32_e32 v42, 0
	v_mov_b32_e32 v43, 0
	v_mov_b32_e32 v44, 0
	v_mov_b32_e32 v45, 0
	v_mov_b32_e32 v46, 0
	v_mov_b32_e32 v47, 0
	v_mov_b32_e32 v48, 0
	v_mov_b32_e32 v49, 0
	v_mov_b32_e32 v50, 0
	v_mov_b32_e32 v51, 0
	v_mov_b32_e32 v52, 0
	v_mov_b32_e32 v53, 0
	v_mov_b32_e32 v54, 0
	v_mov_b32_e32 v55, 0
	v_mov_b32_e32 v56, 0
	v_mov_b32_e32 v57, 0
	v_mov_b32_e32 v58, 0
	v_mov_b32_e32 v59, 0
	v_mov_b32_e32 v60, 0
	v_mov_b32_e32 v61, 0
	v_mov_b32_e32 v62, 0
	v_mov_b32_e32 v63, 0
	v_mov_b32_e32 v64, 0
	v_mov_b32_e32 v65, 0
	v_mov_b32_e32 v66, 0
	v_mov_b32_e32 v67, 0
	v_mov_b32_e32 v68, 0
	v_mov_b32_e32 v69, 0
	v_mov_b32_e32 v70, 0
	v_mov_b32_e32 v71, 0
	v_mov_b32_e32 v72, 0
	v_mov_b32_e32 v73, 0
	v_mov_b32_e32 v74, 0
	v_mov_b32_e32 v75, 0
	v_mov_b32_e32 v76, 0
	v_mov_b32_e32 v77, 0
	v_mov_b32_e32 v78, 0
	v_mov_b32_e32 v79, 0
	v_mov_b32_e32 v80, 0
	v_mov_b32_e32 v81, 0
	v_mov_b32_e32 v82, 0
	v_mov_b32_e32 v83, 0
	v_mov_b32_e32 v84, 0
	v_mov_b32_e32 v85, 0
	v_mov_b32_e32 v86, 0
	v_mov_b32_e32 v87, 0
	v_mov_b32_e32 v88, 0
	v_mov_b32_e32 v89, 0
	v_mov_b32_e32 v90, 0
	v_mov_b32_e32 v91, 0
	v_mov_b32_e32 v92, 0
	v_mov_b32_e32 v93, 0
	v_mov_b32_e32 v94, 0
	v_mov_b32_e32 v95, 0
	v_mov_b32_e32 v96, 0
	v_mov_b32_e32 v97, 0
	v_mov_b32_e32 v98, 0
	v_mov_b32_e32 v99, 0
	s_mov_b32 s34, 0
	s_add_u32 s35, s35, s52
	s_cmp_ge_u32 s31, s30
	s_cbranch_scc1 .Lgm_f2_exit

.Lgm_wo_join:
	s_waitcnt lgkmcnt(13)
	v_mfma_f32_16x16x32_bf16 v[4:7], v[100:103], v[124:127], v[4:7]
	v_mfma_f32_16x16x32_bf16 v[20:23], v[104:107], v[124:127], v[20:23]
	v_mfma_f32_16x16x32_bf16 v[36:39], v[108:111], v[124:127], v[36:39]
	v_mfma_f32_16x16x32_bf16 v[52:55], v[112:115], v[124:127], v[52:55]
	v_mfma_f32_16x16x32_bf16 v[68:71], v[116:119], v[124:127], v[68:71]
	v_mfma_f32_16x16x32_bf16 v[84:87], v[120:123], v[124:127], v[84:87]
	s_waitcnt lgkmcnt(12)
	s_nop 0
	v_mfma_f32_16x16x32_bf16 v[8:11], v[100:103], v[128:131], v[8:11]
	v_mfma_f32_16x16x32_bf16 v[24:27], v[104:107], v[128:131], v[24:27]
	v_mfma_f32_16x16x32_bf16 v[40:43], v[108:111], v[128:131], v[40:43]
	v_mfma_f32_16x16x32_bf16 v[56:59], v[112:115], v[128:131], v[56:59]
	v_mfma_f32_16x16x32_bf16 v[72:75], v[116:119], v[128:131], v[72:75]
	v_mfma_f32_16x16x32_bf16 v[88:91], v[120:123], v[128:131], v[88:91]
	s_waitcnt lgkmcnt(11)
	s_nop 0
	v_mfma_f32_16x16x32_bf16 v[12:15], v[100:103], v[132:135], v[12:15]
	v_mfma_f32_16x16x32_bf16 v[28:31], v[104:107], v[132:135], v[28:31]
	v_mfma_f32_16x16x32_bf16 v[44:47], v[108:111], v[132:135], v[44:47]
	v_mfma_f32_16x16x32_bf16 v[60:63], v[112:115], v[132:135], v[60:63]
	v_mfma_f32_16x16x32_bf16 v[76:79], v[116:119], v[132:135], v[76:79]
	v_mfma_f32_16x16x32_bf16 v[92:95], v[120:123], v[132:135], v[92:95]
	s_waitcnt lgkmcnt(10)
	s_nop 0
	v_mfma_f32_16x16x32_bf16 v[16:19], v[100:103], v[136:139], v[16:19]
	v_mfma_f32_16x16x32_bf16 v[32:35], v[104:107], v[136:139], v[32:35]
	v_mfma_f32_16x16x32_bf16 v[48:51], v[108:111], v[136:139], v[48:51]
	v_mfma_f32_16x16x32_bf16 v[64:67], v[112:115], v[136:139], v[64:67]
	v_mfma_f32_16x16x32_bf16 v[80:83], v[116:119], v[136:139], v[80:83]
	v_mfma_f32_16x16x32_bf16 v[96:99], v[120:123], v[136:139], v[96:99]
	s_waitcnt lgkmcnt(0)
	s_add_u32 s34, s34, 1
	s_add_u32 s31, s31, 1
	s_cmp_lt_u32 s34, 16
	s_cbranch_scc1 .Lgm_wo_rot
	s_nop 0
	v_mfma_f32_16x16x32_bf16 v[4:7], v[140:143], v[164:167], v[4:7]
	v_mfma_f32_16x16x32_bf16 v[20:23], v[144:147], v[164:167], v[20:23]
	v_mfma_f32_16x16x32_bf16 v[36:39], v[148:151], v[164:167], v[36:39]
	v_mfma_f32_16x16x32_bf16 v[52:55], v[152:155], v[164:167], v[52:55]
	v_mfma_f32_16x16x32_bf16 v[68:71], v[156:159], v[164:167], v[68:71]
	v_mfma_f32_16x16x32_bf16 v[84:87], v[160:163], v[164:167], v[84:87]
	v_mfma_f32_16x16x32_bf16 v[8:11], v[140:143], v[168:171], v[8:11]
	v_mfma_f32_16x16x32_bf16 v[24:27], v[144:147], v[168:171], v[24:27]
	v_mfma_f32_16x16x32_bf16 v[40:43], v[148:151], v[168:171], v[40:43]
	v_mfma_f32_16x16x32_bf16 v[56:59], v[152:155], v[168:171], v[56:59]
	v_mfma_f32_16x16x32_bf16 v[72:75], v[156:159], v[168:171], v[72:75]
	v_mfma_f32_16x16x32_bf16 v[88:91], v[160:163], v[168:171], v[88:91]
	v_mfma_f32_16x16x32_bf16 v[12:15], v[140:143], v[172:175], v[12:15]
	v_mfma_f32_16x16x32_bf16 v[28:31], v[144:147], v[172:175], v[28:31]
	v_mfma_f32_16x16x32_bf16 v[44:47], v[148:151], v[172:175], v[44:47]
	v_mfma_f32_16x16x32_bf16 v[60:63], v[152:155], v[172:175], v[60:63]
	v_mfma_f32_16x16x32_bf16 v[76:79], v[156:159], v[172:175], v[76:79]
	v_mfma_f32_16x16x32_bf16 v[92:95], v[160:163], v[172:175], v[92:95]
	v_mfma_f32_16x16x32_bf16 v[16:19], v[140:143], v[176:179], v[16:19]
	v_mfma_f32_16x16x32_bf16 v[32:35], v[144:147], v[176:179], v[32:35]
	v_mfma_f32_16x16x32_bf16 v[48:51], v[148:151], v[176:179], v[48:51]
	v_mfma_f32_16x16x32_bf16 v[64:67], v[152:155], v[176:179], v[64:67]
	v_mfma_f32_16x16x32_bf16 v[80:83], v[156:159], v[176:179], v[80:83]
	v_mfma_f32_16x16x32_bf16 v[96:99], v[160:163], v[176:179], v[96:99]
	s_and_b32 s6, s35, 31
	s_mul_i32 s6, s6, 192
	s_lshr_b32 s7, s35, 5
	s_lshl_b32 s7, s7, 7
	s_nop 7
	s_mul_i32 s4, s6, 0x1000
	s_lshl_b32 s5, s7, 2
	s_add_u32 s4, s4, s5
	v_add_u32_e32 v197, s4, v205
	v_add_u32_e32 v192, s6, v190
	v_lshl_add_u32 v193, s7, 2, v191
	s_sub_i32 s4, s6, 0xc00
	s_max_i32 s4, s4, 0
	s_lshr_b32 s4, s4, 10
	s_add_i32 s5, s6, -2881
	s_max_i32 s5, s5, 0
	s_lshr_b32 s5, s5, 10
	s_movk_i32 s7, 0x1400
	s_cmp_eq_u32 s4, 0
	s_cselect_b32 s7, 0x1000, s7
	s_mul_i32 s4, s4, 0x6000
	s_mul_i32 s5, s5, 0x6000
	v_mov_b32_e32 v194, v197
	v_add_u32_e32 v195, 0, v192
	v_cmp_gt_u32_e32 vcc, 0x1000, v195
	v_mov_b32_e32 v0, s98
	v_mov_b32_e32 v1, s99
	v_mov_b32_e32 v3, s58
	v_cndmask_b32_e32 v0, v0, v3, vcc
	v_mov_b32_e32 v3, s59
	v_cndmask_b32_e32 v1, v1, v3, vcc
	v_add_co_u32_e32 v0, vcc, v0, v194
	s_nop 1
	v_addc_co_u32_e32 v1, vcc, 0, v1, vcc
	global_load_dwordx4 v[100:103], v[0:1], off
	v_add_u32_e32 v194, 0x4000, v194
	v_add_u32_e32 v195, 4, v192
	v_cmp_gt_u32_e32 vcc, 0x1000, v195
	v_mov_b32_e32 v0, s98
	v_mov_b32_e32 v1, s99
	v_mov_b32_e32 v3, s58
	v_cndmask_b32_e32 v0, v0, v3, vcc
	v_mov_b32_e32 v3, s59
	v_cndmask_b32_e32 v1, v1, v3, vcc
	v_add_co_u32_e32 v0, vcc, v0, v194
	s_nop 1
	v_addc_co_u32_e32 v1, vcc, 0, v1, vcc
	global_load_dwordx4 v[104:107], v[0:1], off
	v_add_u32_e32 v194, 0x4000, v194
	v_add_u32_e32 v195, 8, v192
	v_cmp_gt_u32_e32 vcc, 0x1000, v195
	v_mov_b32_e32 v0, s98
	v_mov_b32_e32 v1, s99
	v_mov_b32_e32 v3, s58
	v_cndmask_b32_e32 v0, v0, v3, vcc
	v_mov_b32_e32 v3, s59
	v_cndmask_b32_e32 v1, v1, v3, vcc
	v_add_co_u32_e32 v0, vcc, v0, v194
	s_nop 1
	v_addc_co_u32_e32 v1, vcc, 0, v1, vcc
	global_load_dwordx4 v[108:111], v[0:1], off
	v_add_u32_e32 v194, 0x4000, v194
	v_add_u32_e32 v195, 12, v192
	v_cmp_gt_u32_e32 vcc, 0x1000, v195
	v_mov_b32_e32 v0, s98
	v_mov_b32_e32 v1, s99
	v_mov_b32_e32 v3, s58
	v_cndmask_b32_e32 v0, v0, v3, vcc
	v_mov_b32_e32 v3, s59
	v_cndmask_b32_e32 v1, v1, v3, vcc
	v_add_co_u32_e32 v0, vcc, v0, v194
	s_nop 1
	v_addc_co_u32_e32 v1, vcc, 0, v1, vcc
	global_load_dwordx4 v[112:115], v[0:1], off
	v_add_u32_e32 v194, 0x4000, v194
	v_add_u32_e32 v195, 16, v192
	v_cmp_gt_u32_e32 vcc, 0x1000, v195
	v_mov_b32_e32 v0, s98
	v_mov_b32_e32 v1, s99
	v_mov_b32_e32 v3, s58
	v_cndmask_b32_e32 v0, v0, v3, vcc
	v_mov_b32_e32 v3, s59
	v_cndmask_b32_e32 v1, v1, v3, vcc
	v_add_co_u32_e32 v0, vcc, v0, v194
	s_nop 1
	v_addc_co_u32_e32 v1, vcc, 0, v1, vcc
	global_load_dwordx4 v[116:119], v[0:1], off
	v_add_u32_e32 v194, 0x4000, v194
	v_add_u32_e32 v195, 20, v192
	v_cmp_gt_u32_e32 vcc, 0x1000, v195
	v_mov_b32_e32 v0, s98
	v_mov_b32_e32 v1, s99
	v_mov_b32_e32 v3, s58
	v_cndmask_b32_e32 v0, v0, v3, vcc
	v_mov_b32_e32 v3, s59
	v_cndmask_b32_e32 v1, v1, v3, vcc
	v_add_co_u32_e32 v0, vcc, v0, v194
	s_nop 1
	v_addc_co_u32_e32 v1, vcc, 0, v1, vcc
	global_load_dwordx4 v[120:123], v[0:1], off
	v_add_u32_e32 v194, 0x4000, v194
	v_add_u32_e32 v195, 24, v192
	v_cmp_gt_u32_e32 vcc, 0x1000, v195
	v_mov_b32_e32 v0, s98
	v_mov_b32_e32 v1, s99
	v_mov_b32_e32 v3, s58
	v_cndmask_b32_e32 v0, v0, v3, vcc
	v_mov_b32_e32 v3, s59
	v_cndmask_b32_e32 v1, v1, v3, vcc
	v_add_co_u32_e32 v0, vcc, v0, v194
	s_nop 1
	v_addc_co_u32_e32 v1, vcc, 0, v1, vcc
	global_load_dwordx4 v[124:127], v[0:1], off
	v_add_u32_e32 v194, 0x4000, v194
	v_add_u32_e32 v195, 28, v192
	v_cmp_gt_u32_e32 vcc, 0x1000, v195
	v_mov_b32_e32 v0, s98
	v_mov_b32_e32 v1, s99
	v_mov_b32_e32 v3, s58
	v_cndmask_b32_e32 v0, v0, v3, vcc
	v_mov_b32_e32 v3, s59
	v_cndmask_b32_e32 v1, v1, v3, vcc
	v_add_co_u32_e32 v0, vcc, v0, v194
	s_nop 1
	v_addc_co_u32_e32 v1, vcc, 0, v1, vcc
	global_load_dwordx4 v[128:131], v[0:1], off
	v_add_u32_e32 v194, 0x4000, v194
	v_add_u32_e32 v195, 32, v192
	v_cmp_gt_u32_e32 vcc, 0x1000, v195
	v_mov_b32_e32 v0, s98
	v_mov_b32_e32 v1, s99
	v_mov_b32_e32 v3, s58
	v_cndmask_b32_e32 v0, v0, v3, vcc
	v_mov_b32_e32 v3, s59
	v_cndmask_b32_e32 v1, v1, v3, vcc
	v_add_co_u32_e32 v0, vcc, v0, v194
	s_nop 1
	v_addc_co_u32_e32 v1, vcc, 0, v1, vcc
	global_load_dwordx4 v[132:135], v[0:1], off
	v_add_u32_e32 v194, 0x4000, v194
	v_add_u32_e32 v195, 36, v192
	v_cmp_gt_u32_e32 vcc, 0x1000, v195
	v_mov_b32_e32 v0, s98
	v_mov_b32_e32 v1, s99
	v_mov_b32_e32 v3, s58
	v_cndmask_b32_e32 v0, v0, v3, vcc
	v_mov_b32_e32 v3, s59
	v_cndmask_b32_e32 v1, v1, v3, vcc
	v_add_co_u32_e32 v0, vcc, v0, v194
	s_nop 1
	v_addc_co_u32_e32 v1, vcc, 0, v1, vcc
	global_load_dwordx4 v[136:139], v[0:1], off
	v_add_u32_e32 v194, 0x4000, v194
	v_add_u32_e32 v195, 40, v192
	v_cmp_gt_u32_e32 vcc, 0x1000, v195
	v_mov_b32_e32 v0, s98
	v_mov_b32_e32 v1, s99
	v_mov_b32_e32 v3, s58
	v_cndmask_b32_e32 v0, v0, v3, vcc
	v_mov_b32_e32 v3, s59
	v_cndmask_b32_e32 v1, v1, v3, vcc
	v_add_co_u32_e32 v0, vcc, v0, v194
	s_nop 1
	v_addc_co_u32_e32 v1, vcc, 0, v1, vcc
	global_load_dwordx4 v[140:143], v[0:1], off
	v_add_u32_e32 v194, 0x4000, v194
	v_add_u32_e32 v195, 44, v192
	v_cmp_gt_u32_e32 vcc, 0x1000, v195
	v_mov_b32_e32 v0, s98
	v_mov_b32_e32 v1, s99
	v_mov_b32_e32 v3, s58
	v_cndmask_b32_e32 v0, v0, v3, vcc
	v_mov_b32_e32 v3, s59
	v_cndmask_b32_e32 v1, v1, v3, vcc
	v_add_co_u32_e32 v0, vcc, v0, v194
	s_nop 1
	v_addc_co_u32_e32 v1, vcc, 0, v1, vcc
	global_load_dwordx4 v[144:147], v[0:1], off
	v_add_u32_e32 v194, 0x4000, v194
	v_add_u32_e32 v195, s4, v193
	global_load_dwordx4 v[148:151], v195, s[100:101]
	v_add_u32_e32 v195, s5, v193
	global_load_dwordx4 v[152:155], v195, s[100:101]
	ds_write_b32 v203, v4 offset:0
	ds_write_b32 v203, v5 offset:272
	ds_write_b32 v203, v6 offset:544
	ds_write_b32 v203, v7 offset:816
	ds_write_b32 v203, v8 offset:64
	ds_write_b32 v203, v9 offset:336
	ds_write_b32 v203, v10 offset:608
	ds_write_b32 v203, v11 offset:880
	ds_write_b32 v203, v12 offset:128
	ds_write_b32 v203, v13 offset:400
	ds_write_b32 v203, v14 offset:672
	ds_write_b32 v203, v15 offset:944
	ds_write_b32 v203, v16 offset:192
	ds_write_b32 v203, v17 offset:464
	ds_write_b32 v203, v18 offset:736
	ds_write_b32 v203, v19 offset:1008
	s_waitcnt lgkmcnt(0)
	ds_read_b128 v[156:159], v204 offset:0
	ds_read_b128 v[160:163], v204 offset:1088
	ds_read_b128 v[164:167], v204 offset:2176
	ds_read_b128 v[168:171], v204 offset:3264
	s_waitcnt lgkmcnt(0)
	v_add_u32_e32 v195, 48, v192
	v_cmp_gt_u32_e32 vcc, 0x1000, v195
	v_mov_b32_e32 v0, s98
	v_mov_b32_e32 v1, s99
	v_mov_b32_e32 v3, s58
	v_cndmask_b32_e32 v0, v0, v3, vcc
	v_mov_b32_e32 v3, s59
	v_cndmask_b32_e32 v1, v1, v3, vcc
	v_add_co_u32_e32 v0, vcc, v0, v194
	s_nop 1
	v_addc_co_u32_e32 v1, vcc, 0, v1, vcc
	global_load_dwordx4 v[4:7], v[0:1], off
	v_add_u32_e32 v194, 0x4000, v194
	v_add_u32_e32 v195, 52, v192
	v_cmp_gt_u32_e32 vcc, 0x1000, v195
	v_mov_b32_e32 v0, s98
	v_mov_b32_e32 v1, s99
	v_mov_b32_e32 v3, s58
	v_cndmask_b32_e32 v0, v0, v3, vcc
	v_mov_b32_e32 v3, s59
	v_cndmask_b32_e32 v1, v1, v3, vcc
	v_add_co_u32_e32 v0, vcc, v0, v194
	s_nop 1
	v_addc_co_u32_e32 v1, vcc, 0, v1, vcc
	global_load_dwordx4 v[8:11], v[0:1], off
	v_add_u32_e32 v194, 0x4000, v194
	v_add_u32_e32 v195, 56, v192
	v_cmp_gt_u32_e32 vcc, 0x1000, v195
	v_mov_b32_e32 v0, s98
	v_mov_b32_e32 v1, s99
	v_mov_b32_e32 v3, s58
	v_cndmask_b32_e32 v0, v0, v3, vcc
	v_mov_b32_e32 v3, s59
	v_cndmask_b32_e32 v1, v1, v3, vcc
	v_add_co_u32_e32 v0, vcc, v0, v194
	s_nop 1
	v_addc_co_u32_e32 v1, vcc, 0, v1, vcc
	global_load_dwordx4 v[12:15], v[0:1], off
	v_add_u32_e32 v194, 0x4000, v194
	v_add_u32_e32 v195, 60, v192
	v_cmp_gt_u32_e32 vcc, 0x1000, v195
	v_mov_b32_e32 v0, s98
	v_mov_b32_e32 v1, s99
	v_mov_b32_e32 v3, s58
	v_cndmask_b32_e32 v0, v0, v3, vcc
	v_mov_b32_e32 v3, s59
	v_cndmask_b32_e32 v1, v1, v3, vcc
	v_add_co_u32_e32 v0, vcc, v0, v194
	s_nop 1
	v_addc_co_u32_e32 v1, vcc, 0, v1, vcc
	global_load_dwordx4 v[16:19], v[0:1], off
	v_add_u32_e32 v194, 0x4000, v194
	v_add_u32_e32 v195, 0, v192
	v_cmp_le_u32_e32 vcc, s7, v195
	s_waitcnt vmcnt(4)
	v_cndmask_b32_e32 v172, v148, v152, vcc
	v_cndmask_b32_e32 v173, v149, v153, vcc
	v_cndmask_b32_e32 v174, v150, v154, vcc
	v_cndmask_b32_e32 v175, v151, v155, vcc
	v_fmac_f32_e32 v100, v172, v156
	v_fmac_f32_e32 v101, v173, v157
	v_fmac_f32_e32 v102, v174, v158
	v_fmac_f32_e32 v103, v175, v159
	global_store_dwordx4 v197, v[100:103], s[56:57] sc0 sc1
	v_add_u32_e32 v197, 0x4000, v197
	v_add_u32_e32 v195, 4, v192
	v_cmp_le_u32_e32 vcc, s7, v195
	s_waitcnt vmcnt(5)
	s_waitcnt lgkmcnt(2)
	v_cndmask_b32_e32 v172, v148, v152, vcc
	v_cndmask_b32_e32 v173, v149, v153, vcc
	v_cndmask_b32_e32 v174, v150, v154, vcc
	v_cndmask_b32_e32 v175, v151, v155, vcc
	v_fmac_f32_e32 v104, v172, v160
	v_fmac_f32_e32 v105, v173, v161
	v_fmac_f32_e32 v106, v174, v162
	v_fmac_f32_e32 v107, v175, v163
	global_store_dwordx4 v197, v[104:107], s[56:57] sc0 sc1
	v_add_u32_e32 v197, 0x4000, v197
	v_add_u32_e32 v195, 8, v192
	v_cmp_le_u32_e32 vcc, s7, v195
	s_waitcnt vmcnt(6)
	s_waitcnt lgkmcnt(1)
	v_cndmask_b32_e32 v172, v148, v152, vcc
	v_cndmask_b32_e32 v173, v149, v153, vcc
	v_cndmask_b32_e32 v174, v150, v154, vcc
	v_cndmask_b32_e32 v175, v151, v155, vcc
	v_fmac_f32_e32 v108, v172, v164
	v_fmac_f32_e32 v109, v173, v165
	v_fmac_f32_e32 v110, v174, v166
	v_fmac_f32_e32 v111, v175, v167
	global_store_dwordx4 v197, v[108:111], s[56:57] sc0 sc1
	v_add_u32_e32 v197, 0x4000, v197
	v_add_u32_e32 v195, 12, v192
	v_cmp_le_u32_e32 vcc, s7, v195
	s_waitcnt vmcnt(7)
	s_waitcnt lgkmcnt(0)
	v_cndmask_b32_e32 v172, v148, v152, vcc
	v_cndmask_b32_e32 v173, v149, v153, vcc
	v_cndmask_b32_e32 v174, v150, v154, vcc
	v_cndmask_b32_e32 v175, v151, v155, vcc
	v_fmac_f32_e32 v112, v172, v168
	v_fmac_f32_e32 v113, v173, v169
	v_fmac_f32_e32 v114, v174, v170
	v_fmac_f32_e32 v115, v175, v171
	global_store_dwordx4 v197, v[112:115], s[56:57] sc0 sc1
	v_add_u32_e32 v197, 0x4000, v197
	ds_write_b32 v203, v20 offset:0
	ds_write_b32 v203, v21 offset:272
	ds_write_b32 v203, v22 offset:544
	ds_write_b32 v203, v23 offset:816
	ds_write_b32 v203, v24 offset:64
	ds_write_b32 v203, v25 offset:336
	ds_write_b32 v203, v26 offset:608
	ds_write_b32 v203, v27 offset:880
	ds_write_b32 v203, v28 offset:128
	ds_write_b32 v203, v29 offset:400
	ds_write_b32 v203, v30 offset:672
	ds_write_b32 v203, v31 offset:944
	ds_write_b32 v203, v32 offset:192
	ds_write_b32 v203, v33 offset:464
	ds_write_b32 v203, v34 offset:736
	ds_write_b32 v203, v35 offset:1008
	s_waitcnt lgkmcnt(0)
	ds_read_b128 v[156:159], v204 offset:0
	ds_read_b128 v[160:163], v204 offset:1088
	ds_read_b128 v[164:167], v204 offset:2176
	ds_read_b128 v[168:171], v204 offset:3264
	s_waitcnt lgkmcnt(0)
	v_add_u32_e32 v195, 64, v192
	v_cmp_gt_u32_e32 vcc, 0x1000, v195
	v_mov_b32_e32 v0, s98
	v_mov_b32_e32 v1, s99
	v_mov_b32_e32 v3, s58
	v_cndmask_b32_e32 v0, v0, v3, vcc
	v_mov_b32_e32 v3, s59
	v_cndmask_b32_e32 v1, v1, v3, vcc
	v_add_co_u32_e32 v0, vcc, v0, v194
	s_nop 1
	v_addc_co_u32_e32 v1, vcc, 0, v1, vcc
	global_load_dwordx4 v[20:23], v[0:1], off
	v_add_u32_e32 v194, 0x4000, v194
	v_add_u32_e32 v195, 68, v192
	v_cmp_gt_u32_e32 vcc, 0x1000, v195
	v_mov_b32_e32 v0, s98
	v_mov_b32_e32 v1, s99
	v_mov_b32_e32 v3, s58
	v_cndmask_b32_e32 v0, v0, v3, vcc
	v_mov_b32_e32 v3, s59
	v_cndmask_b32_e32 v1, v1, v3, vcc
	v_add_co_u32_e32 v0, vcc, v0, v194
	s_nop 1
	v_addc_co_u32_e32 v1, vcc, 0, v1, vcc
	global_load_dwordx4 v[24:27], v[0:1], off
	v_add_u32_e32 v194, 0x4000, v194
	v_add_u32_e32 v195, 72, v192
	v_cmp_gt_u32_e32 vcc, 0x1000, v195
	v_mov_b32_e32 v0, s98
	v_mov_b32_e32 v1, s99
	v_mov_b32_e32 v3, s58
	v_cndmask_b32_e32 v0, v0, v3, vcc
	v_mov_b32_e32 v3, s59
	v_cndmask_b32_e32 v1, v1, v3, vcc
	v_add_co_u32_e32 v0, vcc, v0, v194
	s_nop 1
	v_addc_co_u32_e32 v1, vcc, 0, v1, vcc
	global_load_dwordx4 v[28:31], v[0:1], off
	v_add_u32_e32 v194, 0x4000, v194
	v_add_u32_e32 v195, 76, v192
	v_cmp_gt_u32_e32 vcc, 0x1000, v195
	v_mov_b32_e32 v0, s98
	v_mov_b32_e32 v1, s99
	v_mov_b32_e32 v3, s58
	v_cndmask_b32_e32 v0, v0, v3, vcc
	v_mov_b32_e32 v3, s59
	v_cndmask_b32_e32 v1, v1, v3, vcc
	v_add_co_u32_e32 v0, vcc, v0, v194
	s_nop 1
	v_addc_co_u32_e32 v1, vcc, 0, v1, vcc
	global_load_dwordx4 v[32:35], v[0:1], off
	v_add_u32_e32 v194, 0x4000, v194
	v_add_u32_e32 v195, 16, v192
	v_cmp_le_u32_e32 vcc, s7, v195
	s_waitcnt vmcnt(12)
	v_cndmask_b32_e32 v172, v148, v152, vcc
	v_cndmask_b32_e32 v173, v149, v153, vcc
	v_cndmask_b32_e32 v174, v150, v154, vcc
	v_cndmask_b32_e32 v175, v151, v155, vcc
	v_fmac_f32_e32 v116, v172, v156
	v_fmac_f32_e32 v117, v173, v157
	v_fmac_f32_e32 v118, v174, v158
	v_fmac_f32_e32 v119, v175, v159
	global_store_dwordx4 v197, v[116:119], s[56:57] sc0 sc1
	v_add_u32_e32 v197, 0x4000, v197
	v_add_u32_e32 v195, 20, v192
	v_cmp_le_u32_e32 vcc, s7, v195
	s_waitcnt vmcnt(13)
	s_waitcnt lgkmcnt(2)
	v_cndmask_b32_e32 v172, v148, v152, vcc
	v_cndmask_b32_e32 v173, v149, v153, vcc
	v_cndmask_b32_e32 v174, v150, v154, vcc
	v_cndmask_b32_e32 v175, v151, v155, vcc
	v_fmac_f32_e32 v120, v172, v160
	v_fmac_f32_e32 v121, v173, v161
	v_fmac_f32_e32 v122, v174, v162
	v_fmac_f32_e32 v123, v175, v163
	global_store_dwordx4 v197, v[120:123], s[56:57] sc0 sc1
	v_add_u32_e32 v197, 0x4000, v197
	v_add_u32_e32 v195, 24, v192
	v_cmp_le_u32_e32 vcc, s7, v195
	s_waitcnt vmcnt(14)
	s_waitcnt lgkmcnt(1)
	v_cndmask_b32_e32 v172, v148, v152, vcc
	v_cndmask_b32_e32 v173, v149, v153, vcc
	v_cndmask_b32_e32 v174, v150, v154, vcc
	v_cndmask_b32_e32 v175, v151, v155, vcc
	v_fmac_f32_e32 v124, v172, v164
	v_fmac_f32_e32 v125, v173, v165
	v_fmac_f32_e32 v126, v174, v166
	v_fmac_f32_e32 v127, v175, v167
	global_store_dwordx4 v197, v[124:127], s[56:57] sc0 sc1
	v_add_u32_e32 v197, 0x4000, v197
	v_add_u32_e32 v195, 28, v192
	v_cmp_le_u32_e32 vcc, s7, v195
	s_waitcnt vmcnt(15)
	s_waitcnt lgkmcnt(0)
	v_cndmask_b32_e32 v172, v148, v152, vcc
	v_cndmask_b32_e32 v173, v149, v153, vcc
	v_cndmask_b32_e32 v174, v150, v154, vcc
	v_cndmask_b32_e32 v175, v151, v155, vcc
	v_fmac_f32_e32 v128, v172, v168
	v_fmac_f32_e32 v129, v173, v169
	v_fmac_f32_e32 v130, v174, v170
	v_fmac_f32_e32 v131, v175, v171
	global_store_dwordx4 v197, v[128:131], s[56:57] sc0 sc1
	v_add_u32_e32 v197, 0x4000, v197
	ds_write_b32 v203, v36 offset:0
	ds_write_b32 v203, v37 offset:272
	ds_write_b32 v203, v38 offset:544
	ds_write_b32 v203, v39 offset:816
	ds_write_b32 v203, v40 offset:64
	ds_write_b32 v203, v41 offset:336
	ds_write_b32 v203, v42 offset:608
	ds_write_b32 v203, v43 offset:880
	ds_write_b32 v203, v44 offset:128
	ds_write_b32 v203, v45 offset:400
	ds_write_b32 v203, v46 offset:672
	ds_write_b32 v203, v47 offset:944
	ds_write_b32 v203, v48 offset:192
	ds_write_b32 v203, v49 offset:464
	ds_write_b32 v203, v50 offset:736
	ds_write_b32 v203, v51 offset:1008
	s_waitcnt lgkmcnt(0)
	ds_read_b128 v[156:159], v204 offset:0
	ds_read_b128 v[160:163], v204 offset:1088
	ds_read_b128 v[164:167], v204 offset:2176
	ds_read_b128 v[168:171], v204 offset:3264
	s_waitcnt lgkmcnt(0)
	v_add_u32_e32 v195, 80, v192
	v_cmp_gt_u32_e32 vcc, 0x1000, v195
	v_mov_b32_e32 v0, s98
	v_mov_b32_e32 v1, s99
	v_mov_b32_e32 v3, s58
	v_cndmask_b32_e32 v0, v0, v3, vcc
	v_mov_b32_e32 v3, s59
	v_cndmask_b32_e32 v1, v1, v3, vcc
	v_add_co_u32_e32 v0, vcc, v0, v194
	s_nop 1
	v_addc_co_u32_e32 v1, vcc, 0, v1, vcc
	global_load_dwordx4 v[36:39], v[0:1], off
	v_add_u32_e32 v194, 0x4000, v194
	v_add_u32_e32 v195, 84, v192
	v_cmp_gt_u32_e32 vcc, 0x1000, v195
	v_mov_b32_e32 v0, s98
	v_mov_b32_e32 v1, s99
	v_mov_b32_e32 v3, s58
	v_cndmask_b32_e32 v0, v0, v3, vcc
	v_mov_b32_e32 v3, s59
	v_cndmask_b32_e32 v1, v1, v3, vcc
	v_add_co_u32_e32 v0, vcc, v0, v194
	s_nop 1
	v_addc_co_u32_e32 v1, vcc, 0, v1, vcc
	global_load_dwordx4 v[40:43], v[0:1], off
	v_add_u32_e32 v194, 0x4000, v194
	v_add_u32_e32 v195, 88, v192
	v_cmp_gt_u32_e32 vcc, 0x1000, v195
	v_mov_b32_e32 v0, s98
	v_mov_b32_e32 v1, s99
	v_mov_b32_e32 v3, s58
	v_cndmask_b32_e32 v0, v0, v3, vcc
	v_mov_b32_e32 v3, s59
	v_cndmask_b32_e32 v1, v1, v3, vcc
	v_add_co_u32_e32 v0, vcc, v0, v194
	s_nop 1
	v_addc_co_u32_e32 v1, vcc, 0, v1, vcc
	global_load_dwordx4 v[44:47], v[0:1], off
	v_add_u32_e32 v194, 0x4000, v194
	v_add_u32_e32 v195, 92, v192
	v_cmp_gt_u32_e32 vcc, 0x1000, v195
	v_mov_b32_e32 v0, s98
	v_mov_b32_e32 v1, s99
	v_mov_b32_e32 v3, s58
	v_cndmask_b32_e32 v0, v0, v3, vcc
	v_mov_b32_e32 v3, s59
	v_cndmask_b32_e32 v1, v1, v3, vcc
	v_add_co_u32_e32 v0, vcc, v0, v194
	s_nop 1
	v_addc_co_u32_e32 v1, vcc, 0, v1, vcc
	global_load_dwordx4 v[48:51], v[0:1], off
	v_add_u32_e32 v194, 0x4000, v194
	v_add_u32_e32 v195, 32, v192
	v_cmp_le_u32_e32 vcc, s7, v195
	s_waitcnt vmcnt(20)
	v_cndmask_b32_e32 v172, v148, v152, vcc
	v_cndmask_b32_e32 v173, v149, v153, vcc
	v_cndmask_b32_e32 v174, v150, v154, vcc
	v_cndmask_b32_e32 v175, v151, v155, vcc
	v_fmac_f32_e32 v132, v172, v156
	v_fmac_f32_e32 v133, v173, v157
	v_fmac_f32_e32 v134, v174, v158
	v_fmac_f32_e32 v135, v175, v159
	global_store_dwordx4 v197, v[132:135], s[56:57] sc0 sc1
	v_add_u32_e32 v197, 0x4000, v197
	v_add_u32_e32 v195, 36, v192
	v_cmp_le_u32_e32 vcc, s7, v195
	s_waitcnt vmcnt(21)
	s_waitcnt lgkmcnt(2)
	v_cndmask_b32_e32 v172, v148, v152, vcc
	v_cndmask_b32_e32 v173, v149, v153, vcc
	v_cndmask_b32_e32 v174, v150, v154, vcc
	v_cndmask_b32_e32 v175, v151, v155, vcc
	v_fmac_f32_e32 v136, v172, v160
	v_fmac_f32_e32 v137, v173, v161
	v_fmac_f32_e32 v138, v174, v162
	v_fmac_f32_e32 v139, v175, v163
	global_store_dwordx4 v197, v[136:139], s[56:57] sc0 sc1
	v_add_u32_e32 v197, 0x4000, v197
	v_add_u32_e32 v195, 40, v192
	v_cmp_le_u32_e32 vcc, s7, v195
	s_waitcnt vmcnt(22)
	s_waitcnt lgkmcnt(1)
	v_cndmask_b32_e32 v172, v148, v152, vcc
	v_cndmask_b32_e32 v173, v149, v153, vcc
	v_cndmask_b32_e32 v174, v150, v154, vcc
	v_cndmask_b32_e32 v175, v151, v155, vcc
	v_fmac_f32_e32 v140, v172, v164
	v_fmac_f32_e32 v141, v173, v165
	v_fmac_f32_e32 v142, v174, v166
	v_fmac_f32_e32 v143, v175, v167
	global_store_dwordx4 v197, v[140:143], s[56:57] sc0 sc1
	v_add_u32_e32 v197, 0x4000, v197
	v_add_u32_e32 v195, 44, v192
	v_cmp_le_u32_e32 vcc, s7, v195
	s_waitcnt vmcnt(23)
	s_waitcnt lgkmcnt(0)
	v_cndmask_b32_e32 v172, v148, v152, vcc
	v_cndmask_b32_e32 v173, v149, v153, vcc
	v_cndmask_b32_e32 v174, v150, v154, vcc
	v_cndmask_b32_e32 v175, v151, v155, vcc
	v_fmac_f32_e32 v144, v172, v168
	v_fmac_f32_e32 v145, v173, v169
	v_fmac_f32_e32 v146, v174, v170
	v_fmac_f32_e32 v147, v175, v171
	global_store_dwordx4 v197, v[144:147], s[56:57] sc0 sc1
	v_add_u32_e32 v197, 0x4000, v197
	ds_write_b32 v203, v52 offset:0
	ds_write_b32 v203, v53 offset:272
	ds_write_b32 v203, v54 offset:544
	ds_write_b32 v203, v55 offset:816
	ds_write_b32 v203, v56 offset:64
	ds_write_b32 v203, v57 offset:336
	ds_write_b32 v203, v58 offset:608
	ds_write_b32 v203, v59 offset:880
	ds_write_b32 v203, v60 offset:128
	ds_write_b32 v203, v61 offset:400
	ds_write_b32 v203, v62 offset:672
	ds_write_b32 v203, v63 offset:944
	ds_write_b32 v203, v64 offset:192
	ds_write_b32 v203, v65 offset:464
	ds_write_b32 v203, v66 offset:736
	ds_write_b32 v203, v67 offset:1008
	s_waitcnt lgkmcnt(0)
	ds_read_b128 v[156:159], v204 offset:0
	ds_read_b128 v[160:163], v204 offset:1088
	ds_read_b128 v[164:167], v204 offset:2176
	ds_read_b128 v[168:171], v204 offset:3264
	v_add_u32_e32 v195, 48, v192
	v_cmp_le_u32_e32 vcc, s7, v195
	s_waitcnt vmcnt(23)
	s_waitcnt lgkmcnt(3)
	v_cndmask_b32_e32 v172, v148, v152, vcc
	v_cndmask_b32_e32 v173, v149, v153, vcc
	v_cndmask_b32_e32 v174, v150, v154, vcc
	v_cndmask_b32_e32 v175, v151, v155, vcc
	v_fmac_f32_e32 v4, v172, v156
	v_fmac_f32_e32 v5, v173, v157
	v_fmac_f32_e32 v6, v174, v158
	v_fmac_f32_e32 v7, v175, v159
	global_store_dwordx4 v197, v[4:7], s[56:57] sc0 sc1
	v_add_u32_e32 v197, 0x4000, v197
	v_add_u32_e32 v195, 52, v192
	v_cmp_le_u32_e32 vcc, s7, v195
	s_waitcnt vmcnt(23)
	s_waitcnt lgkmcnt(2)
	v_cndmask_b32_e32 v172, v148, v152, vcc
	v_cndmask_b32_e32 v173, v149, v153, vcc
	v_cndmask_b32_e32 v174, v150, v154, vcc
	v_cndmask_b32_e32 v175, v151, v155, vcc
	v_fmac_f32_e32 v8, v172, v160
	v_fmac_f32_e32 v9, v173, v161
	v_fmac_f32_e32 v10, v174, v162
	v_fmac_f32_e32 v11, v175, v163
	global_store_dwordx4 v197, v[8:11], s[56:57] sc0 sc1
	v_add_u32_e32 v197, 0x4000, v197
	v_add_u32_e32 v195, 56, v192
	v_cmp_le_u32_e32 vcc, s7, v195
	s_waitcnt vmcnt(23)
	s_waitcnt lgkmcnt(1)
	v_cndmask_b32_e32 v172, v148, v152, vcc
	v_cndmask_b32_e32 v173, v149, v153, vcc
	v_cndmask_b32_e32 v174, v150, v154, vcc
	v_cndmask_b32_e32 v175, v151, v155, vcc
	v_fmac_f32_e32 v12, v172, v164
	v_fmac_f32_e32 v13, v173, v165
	v_fmac_f32_e32 v14, v174, v166
	v_fmac_f32_e32 v15, v175, v167
	global_store_dwordx4 v197, v[12:15], s[56:57] sc0 sc1
	v_add_u32_e32 v197, 0x4000, v197
	v_add_u32_e32 v195, 60, v192
	v_cmp_le_u32_e32 vcc, s7, v195
	s_waitcnt vmcnt(23)
	s_waitcnt lgkmcnt(0)
	v_cndmask_b32_e32 v172, v148, v152, vcc
	v_cndmask_b32_e32 v173, v149, v153, vcc
	v_cndmask_b32_e32 v174, v150, v154, vcc
	v_cndmask_b32_e32 v175, v151, v155, vcc
	v_fmac_f32_e32 v16, v172, v168
	v_fmac_f32_e32 v17, v173, v169
	v_fmac_f32_e32 v18, v174, v170
	v_fmac_f32_e32 v19, v175, v171
	global_store_dwordx4 v197, v[16:19], s[56:57] sc0 sc1
	v_add_u32_e32 v197, 0x4000, v197
	ds_write_b32 v203, v68 offset:0
	ds_write_b32 v203, v69 offset:272
	ds_write_b32 v203, v70 offset:544
	ds_write_b32 v203, v71 offset:816
	ds_write_b32 v203, v72 offset:64
	ds_write_b32 v203, v73 offset:336
	ds_write_b32 v203, v74 offset:608
	ds_write_b32 v203, v75 offset:880
	ds_write_b32 v203, v76 offset:128
	ds_write_b32 v203, v77 offset:400
	ds_write_b32 v203, v78 offset:672
	ds_write_b32 v203, v79 offset:944
	ds_write_b32 v203, v80 offset:192
	ds_write_b32 v203, v81 offset:464
	ds_write_b32 v203, v82 offset:736
	ds_write_b32 v203, v83 offset:1008
	s_waitcnt lgkmcnt(0)
	ds_read_b128 v[156:159], v204 offset:0
	ds_read_b128 v[160:163], v204 offset:1088
	ds_read_b128 v[164:167], v204 offset:2176
	ds_read_b128 v[168:171], v204 offset:3264
	v_add_u32_e32 v195, 64, v192
	v_cmp_le_u32_e32 vcc, s7, v195
	s_waitcnt vmcnt(19)
	s_waitcnt lgkmcnt(3)
	v_cndmask_b32_e32 v172, v148, v152, vcc
	v_cndmask_b32_e32 v173, v149, v153, vcc
	v_cndmask_b32_e32 v174, v150, v154, vcc
	v_cndmask_b32_e32 v175, v151, v155, vcc
	v_fmac_f32_e32 v20, v172, v156
	v_fmac_f32_e32 v21, v173, v157
	v_fmac_f32_e32 v22, v174, v158
	v_fmac_f32_e32 v23, v175, v159
	global_store_dwordx4 v197, v[20:23], s[56:57] sc0 sc1
	v_add_u32_e32 v197, 0x4000, v197
	v_add_u32_e32 v195, 68, v192
	v_cmp_le_u32_e32 vcc, s7, v195
	s_waitcnt vmcnt(19)
	s_waitcnt lgkmcnt(2)
	v_cndmask_b32_e32 v172, v148, v152, vcc
	v_cndmask_b32_e32 v173, v149, v153, vcc
	v_cndmask_b32_e32 v174, v150, v154, vcc
	v_cndmask_b32_e32 v175, v151, v155, vcc
	v_fmac_f32_e32 v24, v172, v160
	v_fmac_f32_e32 v25, v173, v161
	v_fmac_f32_e32 v26, v174, v162
	v_fmac_f32_e32 v27, v175, v163
	global_store_dwordx4 v197, v[24:27], s[56:57] sc0 sc1
	v_add_u32_e32 v197, 0x4000, v197
	v_add_u32_e32 v195, 72, v192
	v_cmp_le_u32_e32 vcc, s7, v195
	s_waitcnt vmcnt(19)
	s_waitcnt lgkmcnt(1)
	v_cndmask_b32_e32 v172, v148, v152, vcc
	v_cndmask_b32_e32 v173, v149, v153, vcc
	v_cndmask_b32_e32 v174, v150, v154, vcc
	v_cndmask_b32_e32 v175, v151, v155, vcc
	v_fmac_f32_e32 v28, v172, v164
	v_fmac_f32_e32 v29, v173, v165
	v_fmac_f32_e32 v30, v174, v166
	v_fmac_f32_e32 v31, v175, v167
	global_store_dwordx4 v197, v[28:31], s[56:57] sc0 sc1
	v_add_u32_e32 v197, 0x4000, v197
	v_add_u32_e32 v195, 76, v192
	v_cmp_le_u32_e32 vcc, s7, v195
	s_waitcnt vmcnt(19)
	s_waitcnt lgkmcnt(0)
	v_cndmask_b32_e32 v172, v148, v152, vcc
	v_cndmask_b32_e32 v173, v149, v153, vcc
	v_cndmask_b32_e32 v174, v150, v154, vcc
	v_cndmask_b32_e32 v175, v151, v155, vcc
	v_fmac_f32_e32 v32, v172, v168
	v_fmac_f32_e32 v33, v173, v169
	v_fmac_f32_e32 v34, v174, v170
	v_fmac_f32_e32 v35, v175, v171
	global_store_dwordx4 v197, v[32:35], s[56:57] sc0 sc1
	v_add_u32_e32 v197, 0x4000, v197
	ds_write_b32 v203, v84 offset:0
	ds_write_b32 v203, v85 offset:272
	ds_write_b32 v203, v86 offset:544
	ds_write_b32 v203, v87 offset:816
	ds_write_b32 v203, v88 offset:64
	ds_write_b32 v203, v89 offset:336
	ds_write_b32 v203, v90 offset:608
	ds_write_b32 v203, v91 offset:880
	ds_write_b32 v203, v92 offset:128
	ds_write_b32 v203, v93 offset:400
	ds_write_b32 v203, v94 offset:672
	ds_write_b32 v203, v95 offset:944
	ds_write_b32 v203, v96 offset:192
	ds_write_b32 v203, v97 offset:464
	ds_write_b32 v203, v98 offset:736
	ds_write_b32 v203, v99 offset:1008
	s_waitcnt lgkmcnt(0)
	ds_read_b128 v[156:159], v204 offset:0
	ds_read_b128 v[160:163], v204 offset:1088
	ds_read_b128 v[164:167], v204 offset:2176
	ds_read_b128 v[168:171], v204 offset:3264
	v_add_u32_e32 v195, 80, v192
	v_cmp_le_u32_e32 vcc, s7, v195
	s_waitcnt vmcnt(15)
	s_waitcnt lgkmcnt(3)
	v_cndmask_b32_e32 v172, v148, v152, vcc
	v_cndmask_b32_e32 v173, v149, v153, vcc
	v_cndmask_b32_e32 v174, v150, v154, vcc
	v_cndmask_b32_e32 v175, v151, v155, vcc
	v_fmac_f32_e32 v36, v172, v156
	v_fmac_f32_e32 v37, v173, v157
	v_fmac_f32_e32 v38, v174, v158
	v_fmac_f32_e32 v39, v175, v159
	global_store_dwordx4 v197, v[36:39], s[56:57] sc0 sc1
	v_add_u32_e32 v197, 0x4000, v197
	v_add_u32_e32 v195, 84, v192
	v_cmp_le_u32_e32 vcc, s7, v195
	s_waitcnt vmcnt(15)
	s_waitcnt lgkmcnt(2)
	v_cndmask_b32_e32 v172, v148, v152, vcc
	v_cndmask_b32_e32 v173, v149, v153, vcc
	v_cndmask_b32_e32 v174, v150, v154, vcc
	v_cndmask_b32_e32 v175, v151, v155, vcc
	v_fmac_f32_e32 v40, v172, v160
	v_fmac_f32_e32 v41, v173, v161
	v_fmac_f32_e32 v42, v174, v162
	v_fmac_f32_e32 v43, v175, v163
	global_store_dwordx4 v197, v[40:43], s[56:57] sc0 sc1
	v_add_u32_e32 v197, 0x4000, v197
	v_add_u32_e32 v195, 88, v192
	v_cmp_le_u32_e32 vcc, s7, v195
	s_waitcnt vmcnt(15)
	s_waitcnt lgkmcnt(1)
	v_cndmask_b32_e32 v172, v148, v152, vcc
	v_cndmask_b32_e32 v173, v149, v153, vcc
	v_cndmask_b32_e32 v174, v150, v154, vcc
	v_cndmask_b32_e32 v175, v151, v155, vcc
	v_fmac_f32_e32 v44, v172, v164
	v_fmac_f32_e32 v45, v173, v165
	v_fmac_f32_e32 v46, v174, v166
	v_fmac_f32_e32 v47, v175, v167
	global_store_dwordx4 v197, v[44:47], s[56:57] sc0 sc1
	v_add_u32_e32 v197, 0x4000, v197
	v_add_u32_e32 v195, 92, v192
	v_cmp_le_u32_e32 vcc, s7, v195
	s_waitcnt vmcnt(15)
	s_waitcnt lgkmcnt(0)
	v_cndmask_b32_e32 v172, v148, v152, vcc
	v_cndmask_b32_e32 v173, v149, v153, vcc
	v_cndmask_b32_e32 v174, v150, v154, vcc
	v_cndmask_b32_e32 v175, v151, v155, vcc
	v_fmac_f32_e32 v48, v172, v168
	v_fmac_f32_e32 v49, v173, v169
	v_fmac_f32_e32 v50, v174, v170
	v_fmac_f32_e32 v51, v175, v171
	global_store_dwordx4 v197, v[48:51], s[56:57] sc0 sc1
	v_add_u32_e32 v197, 0x4000, v197
	v_mov_b32_e32 v4, 0
	v_mov_b32_e32 v5, 0
	v_mov_b32_e32 v6, 0
	v_mov_b32_e32 v7, 0
	v_mov_b32_e32 v8, 0
	v_mov_b32_e32 v9, 0
	v_mov_b32_e32 v10, 0
	v_mov_b32_e32 v11, 0
	v_mov_b32_e32 v12, 0
	v_mov_b32_e32 v13, 0
	v_mov_b32_e32 v14, 0
	v_mov_b32_e32 v15, 0
	v_mov_b32_e32 v16, 0
	v_mov_b32_e32 v17, 0
	v_mov_b32_e32 v18, 0
	v_mov_b32_e32 v19, 0
	v_mov_b32_e32 v20, 0
	v_mov_b32_e32 v21, 0
	v_mov_b32_e32 v22, 0
	v_mov_b32_e32 v23, 0
	v_mov_b32_e32 v24, 0
	v_mov_b32_e32 v25, 0
	v_mov_b32_e32 v26, 0
	v_mov_b32_e32 v27, 0
	v_mov_b32_e32 v28, 0
	v_mov_b32_e32 v29, 0
	v_mov_b32_e32 v30, 0
	v_mov_b32_e32 v31, 0
	v_mov_b32_e32 v32, 0
	v_mov_b32_e32 v33, 0
	v_mov_b32_e32 v34, 0
	v_mov_b32_e32 v35, 0
	v_mov_b32_e32 v36, 0
	v_mov_b32_e32 v37, 0
	v_mov_b32_e32 v38, 0
	v_mov_b32_e32 v39, 0
	v_mov_b32_e32 v40, 0
	v_mov_b32_e32 v41, 0
	v_mov_b32_e32 v42, 0
	v_mov_b32_e32 v43, 0
	v_mov_b32_e32 v44, 0
	v_mov_b32_e32 v45, 0
	v_mov_b32_e32 v46, 0
	v_mov_b32_e32 v47, 0
	v_mov_b32_e32 v48, 0
	v_mov_b32_e32 v49, 0
	v_mov_b32_e32 v50, 0
	v_mov_b32_e32 v51, 0
	v_mov_b32_e32 v52, 0
	v_mov_b32_e32 v53, 0
	v_mov_b32_e32 v54, 0
	v_mov_b32_e32 v55, 0
	v_mov_b32_e32 v56, 0
	v_mov_b32_e32 v57, 0
	v_mov_b32_e32 v58, 0
	v_mov_b32_e32 v59, 0
	v_mov_b32_e32 v60, 0
	v_mov_b32_e32 v61, 0
	v_mov_b32_e32 v62, 0
	v_mov_b32_e32 v63, 0
	v_mov_b32_e32 v64, 0
	v_mov_b32_e32 v65, 0
	v_mov_b32_e32 v66, 0
	v_mov_b32_e32 v67, 0
	v_mov_b32_e32 v68, 0
	v_mov_b32_e32 v69, 0
	v_mov_b32_e32 v70, 0
	v_mov_b32_e32 v71, 0
	v_mov_b32_e32 v72, 0
	v_mov_b32_e32 v73, 0
	v_mov_b32_e32 v74, 0
	v_mov_b32_e32 v75, 0
	v_mov_b32_e32 v76, 0
	v_mov_b32_e32 v77, 0
	v_mov_b32_e32 v78, 0
	v_mov_b32_e32 v79, 0
	v_mov_b32_e32 v80, 0
	v_mov_b32_e32 v81, 0
	v_mov_b32_e32 v82, 0
	v_mov_b32_e32 v83, 0
	v_mov_b32_e32 v84, 0
	v_mov_b32_e32 v85, 0
	v_mov_b32_e32 v86, 0
	v_mov_b32_e32 v87, 0
	v_mov_b32_e32 v88, 0
	v_mov_b32_e32 v89, 0
	v_mov_b32_e32 v90, 0
	v_mov_b32_e32 v91, 0
	v_mov_b32_e32 v92, 0
	v_mov_b32_e32 v93, 0
	v_mov_b32_e32 v94, 0
	v_mov_b32_e32 v95, 0
	v_mov_b32_e32 v96, 0
	v_mov_b32_e32 v97, 0
	v_mov_b32_e32 v98, 0
	v_mov_b32_e32 v99, 0
	s_mov_b32 s34, 0
	s_add_u32 s35, s35, s52
	s_cmp_ge_u32 s31, s30
	s_cbranch_scc1 .Lgm_wo_exit

.Lgm_wi_join:
	s_waitcnt lgkmcnt(13)
	v_mfma_f32_16x16x32_bf16 v[4:7], v[100:103], v[124:127], v[4:7]
	v_mfma_f32_16x16x32_bf16 v[20:23], v[104:107], v[124:127], v[20:23]
	v_mfma_f32_16x16x32_bf16 v[36:39], v[108:111], v[124:127], v[36:39]
	v_mfma_f32_16x16x32_bf16 v[52:55], v[112:115], v[124:127], v[52:55]
	v_mfma_f32_16x16x32_bf16 v[68:71], v[116:119], v[124:127], v[68:71]
	v_mfma_f32_16x16x32_bf16 v[84:87], v[120:123], v[124:127], v[84:87]
	s_waitcnt lgkmcnt(12)
	s_nop 0
	v_mfma_f32_16x16x32_bf16 v[8:11], v[100:103], v[128:131], v[8:11]
	v_mfma_f32_16x16x32_bf16 v[24:27], v[104:107], v[128:131], v[24:27]
	v_mfma_f32_16x16x32_bf16 v[40:43], v[108:111], v[128:131], v[40:43]
	v_mfma_f32_16x16x32_bf16 v[56:59], v[112:115], v[128:131], v[56:59]
	v_mfma_f32_16x16x32_bf16 v[72:75], v[116:119], v[128:131], v[72:75]
	v_mfma_f32_16x16x32_bf16 v[88:91], v[120:123], v[128:131], v[88:91]
	s_waitcnt lgkmcnt(11)
	s_nop 0
	v_mfma_f32_16x16x32_bf16 v[12:15], v[100:103], v[132:135], v[12:15]
	v_mfma_f32_16x16x32_bf16 v[28:31], v[104:107], v[132:135], v[28:31]
	v_mfma_f32_16x16x32_bf16 v[44:47], v[108:111], v[132:135], v[44:47]
	v_mfma_f32_16x16x32_bf16 v[60:63], v[112:115], v[132:135], v[60:63]
	v_mfma_f32_16x16x32_bf16 v[76:79], v[116:119], v[132:135], v[76:79]
	v_mfma_f32_16x16x32_bf16 v[92:95], v[120:123], v[132:135], v[92:95]
	s_waitcnt lgkmcnt(10)
	s_nop 0
	v_mfma_f32_16x16x32_bf16 v[16:19], v[100:103], v[136:139], v[16:19]
	v_mfma_f32_16x16x32_bf16 v[32:35], v[104:107], v[136:139], v[32:35]
	v_mfma_f32_16x16x32_bf16 v[48:51], v[108:111], v[136:139], v[48:51]
	v_mfma_f32_16x16x32_bf16 v[64:67], v[112:115], v[136:139], v[64:67]
	v_mfma_f32_16x16x32_bf16 v[80:83], v[116:119], v[136:139], v[80:83]
	v_mfma_f32_16x16x32_bf16 v[96:99], v[120:123], v[136:139], v[96:99]
	s_waitcnt lgkmcnt(0)
	s_add_u32 s34, s34, 1
	s_add_u32 s31, s31, 1
	s_cmp_lt_u32 s34, 16
	s_cbranch_scc1 .Lgm_wi_rot
	s_nop 0
	v_mfma_f32_16x16x32_bf16 v[4:7], v[140:143], v[164:167], v[4:7]
	v_mfma_f32_16x16x32_bf16 v[20:23], v[144:147], v[164:167], v[20:23]
	v_mfma_f32_16x16x32_bf16 v[36:39], v[148:151], v[164:167], v[36:39]
	v_mfma_f32_16x16x32_bf16 v[52:55], v[152:155], v[164:167], v[52:55]
	v_mfma_f32_16x16x32_bf16 v[68:71], v[156:159], v[164:167], v[68:71]
	v_mfma_f32_16x16x32_bf16 v[84:87], v[160:163], v[164:167], v[84:87]
	v_mfma_f32_16x16x32_bf16 v[8:11], v[140:143], v[168:171], v[8:11]
	v_mfma_f32_16x16x32_bf16 v[24:27], v[144:147], v[168:171], v[24:27]
	v_mfma_f32_16x16x32_bf16 v[40:43], v[148:151], v[168:171], v[40:43]
	v_mfma_f32_16x16x32_bf16 v[56:59], v[152:155], v[168:171], v[56:59]
	v_mfma_f32_16x16x32_bf16 v[72:75], v[156:159], v[168:171], v[72:75]
	v_mfma_f32_16x16x32_bf16 v[88:91], v[160:163], v[168:171], v[88:91]
	v_mfma_f32_16x16x32_bf16 v[12:15], v[140:143], v[172:175], v[12:15]
	v_mfma_f32_16x16x32_bf16 v[28:31], v[144:147], v[172:175], v[28:31]
	v_mfma_f32_16x16x32_bf16 v[44:47], v[148:151], v[172:175], v[44:47]
	v_mfma_f32_16x16x32_bf16 v[60:63], v[152:155], v[172:175], v[60:63]
	v_mfma_f32_16x16x32_bf16 v[76:79], v[156:159], v[172:175], v[76:79]
	v_mfma_f32_16x16x32_bf16 v[92:95], v[160:163], v[172:175], v[92:95]
	v_mfma_f32_16x16x32_bf16 v[16:19], v[140:143], v[176:179], v[16:19]
	v_mfma_f32_16x16x32_bf16 v[32:35], v[144:147], v[176:179], v[32:35]
	v_mfma_f32_16x16x32_bf16 v[48:51], v[148:151], v[176:179], v[48:51]
	v_mfma_f32_16x16x32_bf16 v[64:67], v[152:155], v[176:179], v[64:67]
	v_mfma_f32_16x16x32_bf16 v[80:83], v[156:159], v[176:179], v[80:83]
	v_mfma_f32_16x16x32_bf16 v[96:99], v[160:163], v[176:179], v[96:99]
	s_and_b32 s6, s35, 31
	s_mul_i32 s6, s6, 192
	s_lshr_b32 s7, s35, 5
	s_lshl_b32 s7, s7, 7
	s_nop 7
	s_mul_i32 s4, s6, 0x2440
	s_lshl_b32 s5, s7, 2
	s_add_u32 s4, s4, s5
	v_add_u32_e32 v197, s4, v205
	v_add_u32_e32 v192, s7, v193
	s_mov_b32 s4, 0x910
	v_cmp_gt_u32_e32 vcc, s4, v192
	s_mov_b64 s[4:5], exec
	ds_write_b32 v203, v4 offset:0
	ds_write_b32 v203, v5 offset:272
	ds_write_b32 v203, v6 offset:544
	ds_write_b32 v203, v7 offset:816
	ds_write_b32 v203, v8 offset:64
	ds_write_b32 v203, v9 offset:336
	ds_write_b32 v203, v10 offset:608
	ds_write_b32 v203, v11 offset:880
	ds_write_b32 v203, v12 offset:128
	ds_write_b32 v203, v13 offset:400
	ds_write_b32 v203, v14 offset:672
	ds_write_b32 v203, v15 offset:944
	ds_write_b32 v203, v16 offset:192
	ds_write_b32 v203, v17 offset:464
	ds_write_b32 v203, v18 offset:736
	ds_write_b32 v203, v19 offset:1008
	s_waitcnt lgkmcnt(0)
	ds_read_b128 v[156:159], v204 offset:0
	ds_read_b128 v[160:163], v204 offset:1088
	ds_read_b128 v[164:167], v204 offset:2176
	ds_read_b128 v[168:171], v204 offset:3264
	s_waitcnt lgkmcnt(0)
	s_and_b64 exec, s[4:5], vcc
	global_store_dwordx4 v197, v[156:159], s[56:57] sc0 sc1
	v_add_u32_e32 v197, 0x9100, v197
	global_store_dwordx4 v197, v[160:163], s[56:57] sc0 sc1
	v_add_u32_e32 v197, 0x9100, v197
	global_store_dwordx4 v197, v[164:167], s[56:57] sc0 sc1
	v_add_u32_e32 v197, 0x9100, v197
	global_store_dwordx4 v197, v[168:171], s[56:57] sc0 sc1
	v_add_u32_e32 v197, 0x9100, v197
	s_mov_b64 exec, s[4:5]
	s_nop 1
	ds_write_b32 v203, v20 offset:0
	ds_write_b32 v203, v21 offset:272
	ds_write_b32 v203, v22 offset:544
	ds_write_b32 v203, v23 offset:816
	ds_write_b32 v203, v24 offset:64
	ds_write_b32 v203, v25 offset:336
	ds_write_b32 v203, v26 offset:608
	ds_write_b32 v203, v27 offset:880
	ds_write_b32 v203, v28 offset:128
	ds_write_b32 v203, v29 offset:400
	ds_write_b32 v203, v30 offset:672
	ds_write_b32 v203, v31 offset:944
	ds_write_b32 v203, v32 offset:192
	ds_write_b32 v203, v33 offset:464
	ds_write_b32 v203, v34 offset:736
	ds_write_b32 v203, v35 offset:1008
	s_waitcnt lgkmcnt(0)
	ds_read_b128 v[156:159], v204 offset:0
	ds_read_b128 v[160:163], v204 offset:1088
	ds_read_b128 v[164:167], v204 offset:2176
	ds_read_b128 v[168:171], v204 offset:3264
	s_waitcnt lgkmcnt(0)
	s_and_b64 exec, s[4:5], vcc
	global_store_dwordx4 v197, v[156:159], s[56:57] sc0 sc1
	v_add_u32_e32 v197, 0x9100, v197
	global_store_dwordx4 v197, v[160:163], s[56:57] sc0 sc1
	v_add_u32_e32 v197, 0x9100, v197
	global_store_dwordx4 v197, v[164:167], s[56:57] sc0 sc1
	v_add_u32_e32 v197, 0x9100, v197
	global_store_dwordx4 v197, v[168:171], s[56:57] sc0 sc1
	v_add_u32_e32 v197, 0x9100, v197
	s_mov_b64 exec, s[4:5]
	s_nop 1
	ds_write_b32 v203, v36 offset:0
	ds_write_b32 v203, v37 offset:272
	ds_write_b32 v203, v38 offset:544
	ds_write_b32 v203, v39 offset:816
	ds_write_b32 v203, v40 offset:64
	ds_write_b32 v203, v41 offset:336
	ds_write_b32 v203, v42 offset:608
	ds_write_b32 v203, v43 offset:880
	ds_write_b32 v203, v44 offset:128
	ds_write_b32 v203, v45 offset:400
	ds_write_b32 v203, v46 offset:672
	ds_write_b32 v203, v47 offset:944
	ds_write_b32 v203, v48 offset:192
	ds_write_b32 v203, v49 offset:464
	ds_write_b32 v203, v50 offset:736
	ds_write_b32 v203, v51 offset:1008
	s_waitcnt lgkmcnt(0)
	ds_read_b128 v[156:159], v204 offset:0
	ds_read_b128 v[160:163], v204 offset:1088
	ds_read_b128 v[164:167], v204 offset:2176
	ds_read_b128 v[168:171], v204 offset:3264
	s_waitcnt lgkmcnt(0)
	s_and_b64 exec, s[4:5], vcc
	global_store_dwordx4 v197, v[156:159], s[56:57] sc0 sc1
	v_add_u32_e32 v197, 0x9100, v197
	global_store_dwordx4 v197, v[160:163], s[56:57] sc0 sc1
	v_add_u32_e32 v197, 0x9100, v197
	global_store_dwordx4 v197, v[164:167], s[56:57] sc0 sc1
	v_add_u32_e32 v197, 0x9100, v197
	global_store_dwordx4 v197, v[168:171], s[56:57] sc0 sc1
	v_add_u32_e32 v197, 0x9100, v197
	s_mov_b64 exec, s[4:5]
	s_nop 1
	ds_write_b32 v203, v52 offset:0
	ds_write_b32 v203, v53 offset:272
	ds_write_b32 v203, v54 offset:544
	ds_write_b32 v203, v55 offset:816
	ds_write_b32 v203, v56 offset:64
	ds_write_b32 v203, v57 offset:336
	ds_write_b32 v203, v58 offset:608
	ds_write_b32 v203, v59 offset:880
	ds_write_b32 v203, v60 offset:128
	ds_write_b32 v203, v61 offset:400
	ds_write_b32 v203, v62 offset:672
	ds_write_b32 v203, v63 offset:944
	ds_write_b32 v203, v64 offset:192
	ds_write_b32 v203, v65 offset:464
	ds_write_b32 v203, v66 offset:736
	ds_write_b32 v203, v67 offset:1008
	s_waitcnt lgkmcnt(0)
	ds_read_b128 v[156:159], v204 offset:0
	ds_read_b128 v[160:163], v204 offset:1088
	ds_read_b128 v[164:167], v204 offset:2176
	ds_read_b128 v[168:171], v204 offset:3264
	s_waitcnt lgkmcnt(0)
	s_and_b64 exec, s[4:5], vcc
	global_store_dwordx4 v197, v[156:159], s[56:57] sc0 sc1
	v_add_u32_e32 v197, 0x9100, v197
	global_store_dwordx4 v197, v[160:163], s[56:57] sc0 sc1
	v_add_u32_e32 v197, 0x9100, v197
	global_store_dwordx4 v197, v[164:167], s[56:57] sc0 sc1
	v_add_u32_e32 v197, 0x9100, v197
	global_store_dwordx4 v197, v[168:171], s[56:57] sc0 sc1
	v_add_u32_e32 v197, 0x9100, v197
	s_mov_b64 exec, s[4:5]
	s_nop 1
	ds_write_b32 v203, v68 offset:0
	ds_write_b32 v203, v69 offset:272
	ds_write_b32 v203, v70 offset:544
	ds_write_b32 v203, v71 offset:816
	ds_write_b32 v203, v72 offset:64
	ds_write_b32 v203, v73 offset:336
	ds_write_b32 v203, v74 offset:608
	ds_write_b32 v203, v75 offset:880
	ds_write_b32 v203, v76 offset:128
	ds_write_b32 v203, v77 offset:400
	ds_write_b32 v203, v78 offset:672
	ds_write_b32 v203, v79 offset:944
	ds_write_b32 v203, v80 offset:192
	ds_write_b32 v203, v81 offset:464
	ds_write_b32 v203, v82 offset:736
	ds_write_b32 v203, v83 offset:1008
	s_waitcnt lgkmcnt(0)
	ds_read_b128 v[156:159], v204 offset:0
	ds_read_b128 v[160:163], v204 offset:1088
	ds_read_b128 v[164:167], v204 offset:2176
	ds_read_b128 v[168:171], v204 offset:3264
	s_waitcnt lgkmcnt(0)
	s_and_b64 exec, s[4:5], vcc
	global_store_dwordx4 v197, v[156:159], s[56:57] sc0 sc1
	v_add_u32_e32 v197, 0x9100, v197
	global_store_dwordx4 v197, v[160:163], s[56:57] sc0 sc1
	v_add_u32_e32 v197, 0x9100, v197
	global_store_dwordx4 v197, v[164:167], s[56:57] sc0 sc1
	v_add_u32_e32 v197, 0x9100, v197
	global_store_dwordx4 v197, v[168:171], s[56:57] sc0 sc1
	v_add_u32_e32 v197, 0x9100, v197
	s_mov_b64 exec, s[4:5]
	s_nop 1
	ds_write_b32 v203, v84 offset:0
	ds_write_b32 v203, v85 offset:272
	ds_write_b32 v203, v86 offset:544
	ds_write_b32 v203, v87 offset:816
	ds_write_b32 v203, v88 offset:64
	ds_write_b32 v203, v89 offset:336
	ds_write_b32 v203, v90 offset:608
	ds_write_b32 v203, v91 offset:880
	ds_write_b32 v203, v92 offset:128
	ds_write_b32 v203, v93 offset:400
	ds_write_b32 v203, v94 offset:672
	ds_write_b32 v203, v95 offset:944
	ds_write_b32 v203, v96 offset:192
	ds_write_b32 v203, v97 offset:464
	ds_write_b32 v203, v98 offset:736
	ds_write_b32 v203, v99 offset:1008
	s_waitcnt lgkmcnt(0)
	ds_read_b128 v[156:159], v204 offset:0
	ds_read_b128 v[160:163], v204 offset:1088
	ds_read_b128 v[164:167], v204 offset:2176
	ds_read_b128 v[168:171], v204 offset:3264
	s_waitcnt lgkmcnt(0)
	s_and_b64 exec, s[4:5], vcc
	global_store_dwordx4 v197, v[156:159], s[56:57] sc0 sc1
	v_add_u32_e32 v197, 0x9100, v197
	global_store_dwordx4 v197, v[160:163], s[56:57] sc0 sc1
	v_add_u32_e32 v197, 0x9100, v197
	global_store_dwordx4 v197, v[164:167], s[56:57] sc0 sc1
	v_add_u32_e32 v197, 0x9100, v197
	global_store_dwordx4 v197, v[168:171], s[56:57] sc0 sc1
	v_add_u32_e32 v197, 0x9100, v197
	s_mov_b64 exec, s[4:5]
	s_nop 1
	v_mov_b32_e32 v4, 0
	v_mov_b32_e32 v5, 0
	v_mov_b32_e32 v6, 0
	v_mov_b32_e32 v7, 0
	v_mov_b32_e32 v8, 0
	v_mov_b32_e32 v9, 0
	v_mov_b32_e32 v10, 0
	v_mov_b32_e32 v11, 0
	v_mov_b32_e32 v12, 0
	v_mov_b32_e32 v13, 0
	v_mov_b32_e32 v14, 0
	v_mov_b32_e32 v15, 0
	v_mov_b32_e32 v16, 0
	v_mov_b32_e32 v17, 0
	v_mov_b32_e32 v18, 0
	v_mov_b32_e32 v19, 0
	v_mov_b32_e32 v20, 0
	v_mov_b32_e32 v21, 0
	v_mov_b32_e32 v22, 0
	v_mov_b32_e32 v23, 0
	v_mov_b32_e32 v24, 0
	v_mov_b32_e32 v25, 0
	v_mov_b32_e32 v26, 0
	v_mov_b32_e32 v27, 0
	v_mov_b32_e32 v28, 0
	v_mov_b32_e32 v29, 0
	v_mov_b32_e32 v30, 0
	v_mov_b32_e32 v31, 0
	v_mov_b32_e32 v32, 0
	v_mov_b32_e32 v33, 0
	v_mov_b32_e32 v34, 0
	v_mov_b32_e32 v35, 0
	v_mov_b32_e32 v36, 0
	v_mov_b32_e32 v37, 0
	v_mov_b32_e32 v38, 0
	v_mov_b32_e32 v39, 0
	v_mov_b32_e32 v40, 0
	v_mov_b32_e32 v41, 0
	v_mov_b32_e32 v42, 0
	v_mov_b32_e32 v43, 0
	v_mov_b32_e32 v44, 0
	v_mov_b32_e32 v45, 0
	v_mov_b32_e32 v46, 0
	v_mov_b32_e32 v47, 0
	v_mov_b32_e32 v48, 0
	v_mov_b32_e32 v49, 0
	v_mov_b32_e32 v50, 0
	v_mov_b32_e32 v51, 0
	v_mov_b32_e32 v52, 0
	v_mov_b32_e32 v53, 0
	v_mov_b32_e32 v54, 0
	v_mov_b32_e32 v55, 0
	v_mov_b32_e32 v56, 0
	v_mov_b32_e32 v57, 0
	v_mov_b32_e32 v58, 0
	v_mov_b32_e32 v59, 0
	v_mov_b32_e32 v60, 0
	v_mov_b32_e32 v61, 0
	v_mov_b32_e32 v62, 0
	v_mov_b32_e32 v63, 0
	v_mov_b32_e32 v64, 0
	v_mov_b32_e32 v65, 0
	v_mov_b32_e32 v66, 0
	v_mov_b32_e32 v67, 0
	v_mov_b32_e32 v68, 0
	v_mov_b32_e32 v69, 0
	v_mov_b32_e32 v70, 0
	v_mov_b32_e32 v71, 0
	v_mov_b32_e32 v72, 0
	v_mov_b32_e32 v73, 0
	v_mov_b32_e32 v74, 0
	v_mov_b32_e32 v75, 0
	v_mov_b32_e32 v76, 0
	v_mov_b32_e32 v77, 0
	v_mov_b32_e32 v78, 0
	v_mov_b32_e32 v79, 0
	v_mov_b32_e32 v80, 0
	v_mov_b32_e32 v81, 0
	v_mov_b32_e32 v82, 0
	v_mov_b32_e32 v83, 0
	v_mov_b32_e32 v84, 0
	v_mov_b32_e32 v85, 0
	v_mov_b32_e32 v86, 0
	v_mov_b32_e32 v87, 0
	v_mov_b32_e32 v88, 0
	v_mov_b32_e32 v89, 0
	v_mov_b32_e32 v90, 0
	v_mov_b32_e32 v91, 0
	v_mov_b32_e32 v92, 0
	v_mov_b32_e32 v93, 0
	v_mov_b32_e32 v94, 0
	v_mov_b32_e32 v95, 0
	v_mov_b32_e32 v96, 0
	v_mov_b32_e32 v97, 0
	v_mov_b32_e32 v98, 0
	v_mov_b32_e32 v99, 0
	s_mov_b32 s34, 0
	s_add_u32 s35, s35, s52
	s_cmp_ge_u32 s31, s30
	s_cbranch_scc1 .Lgm_wi_exit

.Lgm_glu_join:
	s_waitcnt lgkmcnt(13)
	v_mfma_f32_16x16x32_bf16 v[4:7], v[100:103], v[124:127], v[4:7]
	v_mfma_f32_16x16x32_bf16 v[20:23], v[104:107], v[124:127], v[20:23]
	v_mfma_f32_16x16x32_bf16 v[36:39], v[108:111], v[124:127], v[36:39]
	v_mfma_f32_16x16x32_bf16 v[52:55], v[112:115], v[124:127], v[52:55]
	v_mfma_f32_16x16x32_bf16 v[68:71], v[116:119], v[124:127], v[68:71]
	v_mfma_f32_16x16x32_bf16 v[84:87], v[120:123], v[124:127], v[84:87]
	s_waitcnt lgkmcnt(12)
	s_nop 0
	v_mfma_f32_16x16x32_bf16 v[8:11], v[100:103], v[128:131], v[8:11]
	v_mfma_f32_16x16x32_bf16 v[24:27], v[104:107], v[128:131], v[24:27]
	v_mfma_f32_16x16x32_bf16 v[40:43], v[108:111], v[128:131], v[40:43]
	v_mfma_f32_16x16x32_bf16 v[56:59], v[112:115], v[128:131], v[56:59]
	v_mfma_f32_16x16x32_bf16 v[72:75], v[116:119], v[128:131], v[72:75]
	v_mfma_f32_16x16x32_bf16 v[88:91], v[120:123], v[128:131], v[88:91]
	s_waitcnt lgkmcnt(11)
	s_nop 0
	v_mfma_f32_16x16x32_bf16 v[12:15], v[100:103], v[132:135], v[12:15]
	v_mfma_f32_16x16x32_bf16 v[28:31], v[104:107], v[132:135], v[28:31]
	v_mfma_f32_16x16x32_bf16 v[44:47], v[108:111], v[132:135], v[44:47]
	v_mfma_f32_16x16x32_bf16 v[60:63], v[112:115], v[132:135], v[60:63]
	v_mfma_f32_16x16x32_bf16 v[76:79], v[116:119], v[132:135], v[76:79]
	v_mfma_f32_16x16x32_bf16 v[92:95], v[120:123], v[132:135], v[92:95]
	s_waitcnt lgkmcnt(10)
	s_nop 0
	v_mfma_f32_16x16x32_bf16 v[16:19], v[100:103], v[136:139], v[16:19]
	v_mfma_f32_16x16x32_bf16 v[32:35], v[104:107], v[136:139], v[32:35]
	v_mfma_f32_16x16x32_bf16 v[48:51], v[108:111], v[136:139], v[48:51]
	v_mfma_f32_16x16x32_bf16 v[64:67], v[112:115], v[136:139], v[64:67]
	v_mfma_f32_16x16x32_bf16 v[80:83], v[116:119], v[136:139], v[80:83]
	v_mfma_f32_16x16x32_bf16 v[96:99], v[120:123], v[136:139], v[96:99]
	s_waitcnt lgkmcnt(0)
	s_add_u32 s34, s34, 1
	s_add_u32 s31, s31, 1
	s_cmp_lt_u32 s34, 4
	s_cbranch_scc1 .Lgm_glu_rot
	s_nop 0
	v_mfma_f32_16x16x32_bf16 v[4:7], v[140:143], v[164:167], v[4:7]
	v_mfma_f32_16x16x32_bf16 v[20:23], v[144:147], v[164:167], v[20:23]
	v_mfma_f32_16x16x32_bf16 v[36:39], v[148:151], v[164:167], v[36:39]
	v_mfma_f32_16x16x32_bf16 v[52:55], v[152:155], v[164:167], v[52:55]
	v_mfma_f32_16x16x32_bf16 v[68:71], v[156:159], v[164:167], v[68:71]
	v_mfma_f32_16x16x32_bf16 v[84:87], v[160:163], v[164:167], v[84:87]
	v_mfma_f32_16x16x32_bf16 v[8:11], v[140:143], v[168:171], v[8:11]
	v_mfma_f32_16x16x32_bf16 v[24:27], v[144:147], v[168:171], v[24:27]
	v_mfma_f32_16x16x32_bf16 v[40:43], v[148:151], v[168:171], v[40:43]
	v_mfma_f32_16x16x32_bf16 v[56:59], v[152:155], v[168:171], v[56:59]
	v_mfma_f32_16x16x32_bf16 v[72:75], v[156:159], v[168:171], v[72:75]
	v_mfma_f32_16x16x32_bf16 v[88:91], v[160:163], v[168:171], v[88:91]
	v_mfma_f32_16x16x32_bf16 v[12:15], v[140:143], v[172:175], v[12:15]
	v_mfma_f32_16x16x32_bf16 v[28:31], v[144:147], v[172:175], v[28:31]
	v_mfma_f32_16x16x32_bf16 v[44:47], v[148:151], v[172:175], v[44:47]
	v_mfma_f32_16x16x32_bf16 v[60:63], v[152:155], v[172:175], v[60:63]
	v_mfma_f32_16x16x32_bf16 v[76:79], v[156:159], v[172:175], v[76:79]
	v_mfma_f32_16x16x32_bf16 v[92:95], v[160:163], v[172:175], v[92:95]
	v_mfma_f32_16x16x32_bf16 v[16:19], v[140:143], v[176:179], v[16:19]
	v_mfma_f32_16x16x32_bf16 v[32:35], v[144:147], v[176:179], v[32:35]
	v_mfma_f32_16x16x32_bf16 v[48:51], v[148:151], v[176:179], v[48:51]
	v_mfma_f32_16x16x32_bf16 v[64:67], v[152:155], v[176:179], v[64:67]
	v_mfma_f32_16x16x32_bf16 v[80:83], v[156:159], v[176:179], v[80:83]
	v_mfma_f32_16x16x32_bf16 v[96:99], v[160:163], v[176:179], v[96:99]
	s_and_b32 s6, s35, 31
	s_mul_i32 s6, s6, 192
	s_lshr_b32 s7, s35, 5
	s_lshl_b32 s7, s7, 7
	s_nop 7
	s_mul_i32 s4, s6, 0x800
	s_lshl_b32 s5, s7, 1
	s_add_u32 s4, s4, s5
	v_add_u32_e32 v197, s4, v205
	v_lshl_add_u32 v195, s7, 2, v191
	global_load_dwordx4 v[148:151], v195, s[100:101]
	s_lshl_b32 s4, s6, 9
	s_add_u32 s4, s4, s5
	v_lshlrev_b32_e32 v194, 9, v190
	v_lshl_add_u32 v194, v193, 1, v194
	v_add_u32_e32 v194, s4, v194
	global_load_dwordx2 v[100:101], v194, s[98:99]
	v_add_u32_e32 v194, 0x800, v194
	global_load_dwordx2 v[102:103], v194, s[98:99]
	v_add_u32_e32 v194, 0x800, v194
	global_load_dwordx2 v[104:105], v194, s[98:99]
	v_add_u32_e32 v194, 0x800, v194
	global_load_dwordx2 v[106:107], v194, s[98:99]
	v_add_u32_e32 v194, 0x800, v194
	global_load_dwordx2 v[108:109], v194, s[98:99]
	v_add_u32_e32 v194, 0x800, v194
	global_load_dwordx2 v[110:111], v194, s[98:99]
	v_add_u32_e32 v194, 0x800, v194
	global_load_dwordx2 v[112:113], v194, s[98:99]
	v_add_u32_e32 v194, 0x800, v194
	global_load_dwordx2 v[114:115], v194, s[98:99]
	v_add_u32_e32 v194, 0x800, v194
	global_load_dwordx2 v[116:117], v194, s[98:99]
	v_add_u32_e32 v194, 0x800, v194
	global_load_dwordx2 v[118:119], v194, s[98:99]
	v_add_u32_e32 v194, 0x800, v194
	global_load_dwordx2 v[120:121], v194, s[98:99]
	v_add_u32_e32 v194, 0x800, v194
	global_load_dwordx2 v[122:123], v194, s[98:99]
	v_add_u32_e32 v194, 0x800, v194
	global_load_dwordx2 v[124:125], v194, s[98:99]
	v_add_u32_e32 v194, 0x800, v194
	global_load_dwordx2 v[126:127], v194, s[98:99]
	v_add_u32_e32 v194, 0x800, v194
	global_load_dwordx2 v[128:129], v194, s[98:99]
	v_add_u32_e32 v194, 0x800, v194
	global_load_dwordx2 v[130:131], v194, s[98:99]
	v_add_u32_e32 v194, 0x800, v194
	global_load_dwordx2 v[132:133], v194, s[98:99]
	v_add_u32_e32 v194, 0x800, v194
	global_load_dwordx2 v[134:135], v194, s[98:99]
	v_add_u32_e32 v194, 0x800, v194
	global_load_dwordx2 v[136:137], v194, s[98:99]
	v_add_u32_e32 v194, 0x800, v194
	global_load_dwordx2 v[138:139], v194, s[98:99]
	v_add_u32_e32 v194, 0x800, v194
	global_load_dwordx2 v[140:141], v194, s[98:99]
	v_add_u32_e32 v194, 0x800, v194
	global_load_dwordx2 v[142:143], v194, s[98:99]
	v_add_u32_e32 v194, 0x800, v194
	global_load_dwordx2 v[144:145], v194, s[98:99]
	v_add_u32_e32 v194, 0x800, v194
	global_load_dwordx2 v[146:147], v194, s[98:99]
	s_mov_b32 s4, 0
